# LayerNorm-1 + modulate fused into out-proj GEMM epilogue (h1 tile kept in registers across the barrier, tile stats via ws), on top of LN2 fusion
# speedup vs baseline: 1.0186x; 1.0021x over previous
;     __device__ __forceinline__ void operator()(const Acc& acc, const Unit& u, int wr, int wc, int fr, int fq) const {
;     ...
;         for (int bj = 0; bj < 2; ++bj)
; #pragma unroll
;             for (int ai = 0; ai < 2; ++ai) {
;                 f32x4 bsv[4][2];
; #pragma unroll
;                 for (int m = 0; m < 4; ++m)
; #pragma unroll
;                     for (int n = 0; n < 2; ++n) { const size_t off = (size_t)(u.pm * BM + ai * HALF + wr * 64 + m * 16 + fr) * DMODEL + col0 + bj * HALF + n * 16; bsv[m][n] = __builtin_nontemporal_load((const f32x4*)(base + off)); }
; #pragma unroll
;                 for (int m = 0; m < 4; ++m)
; #pragma unroll
;                     for (int n = 0; n < 2; ++n) { const size_t off = (size_t)(u.pm * BM + ai * HALF + wr * 64 + m * 16 + fr) * DMODEL + col0 + bj * HALF + n * 16;
;                         *(f32x4*)(out + off) = bsv[m][n] * ALPHA + gvv[bj][n] * acc[ai][bj][m][n]; } }
.LBB0_906:
	v_lshl_or_b32 v130, s33, 8, v177
	v_lshl_add_u32 v194, s24, 8, v1
	s_ashr_i32 s17, s24, 4
	v_ashrrev_i32_e32 v131, 31, v130
	s_mul_hi_i32 s19, s17, 0xc000
	s_mul_i32 s17, s17, 0xc000
	v_lshlrev_b64 v[174:175], 2, v[130:131]
	s_add_u32 s26, s43, s17
	s_addc_u32 s27, s44, s19
	v_lshl_add_u64 v[218:219], s[6:7], 0, v[174:175]
	v_lshlrev_b32_e32 v220, 13, v194
	v_mov_b32_e32 v221, 0
	v_lshl_add_u64 v[158:159], v[218:219], 0, v[220:221]
	v_lshl_add_u64 v[160:161], s[4:5], 0, v[174:175]
	v_lshl_add_u64 v[160:161], v[160:161], 0, v[220:221]
	v_lshl_add_u64 v[166:167], s[26:27], 0, v[174:175]
	global_load_dwordx4 v[142:145], v[166:167], off
	global_load_dwordx4 v[138:141], v[166:167], off offset:64
	global_load_dwordx4 v[134:137], v[166:167], off offset:512
	global_load_dwordx4 v[130:133], v[166:167], off offset:576
	s_add_u32 s60, s43, 0x19c000
	s_addc_u32 s61, s44, 0
	global_load_dwordx4 v[198:201], v[158:159], off nt
	global_load_dwordx4 v[202:205], v[158:159], off offset:64 nt
	global_load_dwordx4 v[206:209], v[158:159], off offset:512 nt
	global_load_dwordx4 v[210:213], v[158:159], off offset:576 nt
	s_mov_b64 s[56:57], 0x20000
	v_lshl_add_u64 v[162:163], v[158:159], 0, s[56:57]
	global_load_dwordx4 v[222:225], v[162:163], off nt
	global_load_dwordx4 v[226:229], v[162:163], off offset:64 nt
	global_load_dwordx4 v[230:233], v[162:163], off offset:512 nt
	global_load_dwordx4 v[234:237], v[162:163], off offset:576 nt
	s_waitcnt vmcnt(4)
	v_pk_mul_f32 v[198:199], v[198:199], s[14:15] op_sel_hi:[1,0]
	v_pk_mul_f32 v[200:201], v[200:201], s[14:15] op_sel_hi:[1,0]
	v_pk_mul_f32 v[202:203], v[202:203], s[14:15] op_sel_hi:[1,0]
	v_pk_mul_f32 v[204:205], v[204:205], s[14:15] op_sel_hi:[1,0]
	v_pk_mul_f32 v[206:207], v[206:207], s[14:15] op_sel_hi:[1,0]
	v_pk_mul_f32 v[208:209], v[208:209], s[14:15] op_sel_hi:[1,0]
	v_pk_mul_f32 v[210:211], v[210:211], s[14:15] op_sel_hi:[1,0]
	v_pk_mul_f32 v[212:213], v[212:213], s[14:15] op_sel_hi:[1,0]
	v_pk_fma_f32 v[126:127], v[126:127], v[142:143], v[198:199]
	v_pk_fma_f32 v[128:129], v[128:129], v[144:145], v[200:201]
	v_pk_fma_f32 v[122:123], v[122:123], v[138:139], v[202:203]
	v_pk_fma_f32 v[124:125], v[124:125], v[140:141], v[204:205]
	v_pk_fma_f32 v[62:63], v[62:63], v[134:135], v[206:207]
	v_pk_fma_f32 v[64:65], v[64:65], v[136:137], v[208:209]
	v_pk_fma_f32 v[58:59], v[58:59], v[130:131], v[210:211]
	v_pk_fma_f32 v[60:61], v[60:61], v[132:133], v[212:213]
	global_store_dwordx4 v[160:161], v[126:129], off
	global_store_dwordx4 v[160:161], v[122:125], off offset:64
	global_store_dwordx4 v[160:161], v[62:65], off offset:512
	global_store_dwordx4 v[160:161], v[58:61], off offset:576
	s_mov_b64 s[56:57], 0x40000
	v_lshl_add_u64 v[162:163], v[158:159], 0, s[56:57]
	global_load_dwordx4 v[198:201], v[162:163], off nt
	global_load_dwordx4 v[202:205], v[162:163], off offset:64 nt
	global_load_dwordx4 v[206:209], v[162:163], off offset:512 nt
	global_load_dwordx4 v[210:213], v[162:163], off offset:576 nt
	s_waitcnt vmcnt(8)
	v_pk_mul_f32 v[222:223], v[222:223], s[14:15] op_sel_hi:[1,0]
	v_pk_mul_f32 v[224:225], v[224:225], s[14:15] op_sel_hi:[1,0]
	v_pk_mul_f32 v[226:227], v[226:227], s[14:15] op_sel_hi:[1,0]
	v_pk_mul_f32 v[228:229], v[228:229], s[14:15] op_sel_hi:[1,0]
	v_pk_mul_f32 v[230:231], v[230:231], s[14:15] op_sel_hi:[1,0]
	v_pk_mul_f32 v[232:233], v[232:233], s[14:15] op_sel_hi:[1,0]
	v_pk_mul_f32 v[234:235], v[234:235], s[14:15] op_sel_hi:[1,0]
	v_pk_mul_f32 v[236:237], v[236:237], s[14:15] op_sel_hi:[1,0]
	v_pk_fma_f32 v[118:119], v[118:119], v[142:143], v[222:223]
	v_pk_fma_f32 v[120:121], v[120:121], v[144:145], v[224:225]
	v_pk_fma_f32 v[114:115], v[114:115], v[138:139], v[226:227]
	v_pk_fma_f32 v[116:117], v[116:117], v[140:141], v[228:229]
	v_pk_fma_f32 v[54:55], v[54:55], v[134:135], v[230:231]
	v_pk_fma_f32 v[56:57], v[56:57], v[136:137], v[232:233]
	v_pk_fma_f32 v[50:51], v[50:51], v[130:131], v[234:235]
	v_pk_fma_f32 v[52:53], v[52:53], v[132:133], v[236:237]
	s_mov_b64 s[58:59], 0x20000
	v_lshl_add_u64 v[164:165], v[160:161], 0, s[58:59]
	global_store_dwordx4 v[164:165], v[118:121], off
	global_store_dwordx4 v[164:165], v[114:117], off offset:64
	global_store_dwordx4 v[164:165], v[54:57], off offset:512
	global_store_dwordx4 v[164:165], v[50:53], off offset:576
	s_mov_b64 s[56:57], 0x60000
	v_lshl_add_u64 v[162:163], v[158:159], 0, s[56:57]
	global_load_dwordx4 v[222:225], v[162:163], off nt
	global_load_dwordx4 v[226:229], v[162:163], off offset:64 nt
	global_load_dwordx4 v[230:233], v[162:163], off offset:512 nt
	global_load_dwordx4 v[234:237], v[162:163], off offset:576 nt
	s_waitcnt vmcnt(8)
	v_pk_mul_f32 v[198:199], v[198:199], s[14:15] op_sel_hi:[1,0]
	v_pk_mul_f32 v[200:201], v[200:201], s[14:15] op_sel_hi:[1,0]
	v_pk_mul_f32 v[202:203], v[202:203], s[14:15] op_sel_hi:[1,0]
	v_pk_mul_f32 v[204:205], v[204:205], s[14:15] op_sel_hi:[1,0]
	v_pk_mul_f32 v[206:207], v[206:207], s[14:15] op_sel_hi:[1,0]
	v_pk_mul_f32 v[208:209], v[208:209], s[14:15] op_sel_hi:[1,0]
	v_pk_mul_f32 v[210:211], v[210:211], s[14:15] op_sel_hi:[1,0]
	v_pk_mul_f32 v[212:213], v[212:213], s[14:15] op_sel_hi:[1,0]
	v_pk_fma_f32 v[110:111], v[110:111], v[142:143], v[198:199]
	v_pk_fma_f32 v[112:113], v[112:113], v[144:145], v[200:201]
	v_pk_fma_f32 v[106:107], v[106:107], v[138:139], v[202:203]
	v_pk_fma_f32 v[108:109], v[108:109], v[140:141], v[204:205]
	v_pk_fma_f32 v[46:47], v[46:47], v[134:135], v[206:207]
	v_pk_fma_f32 v[48:49], v[48:49], v[136:137], v[208:209]
	v_pk_fma_f32 v[42:43], v[42:43], v[130:131], v[210:211]
	v_pk_fma_f32 v[44:45], v[44:45], v[132:133], v[212:213]
	s_mov_b64 s[58:59], 0x40000
	v_lshl_add_u64 v[164:165], v[160:161], 0, s[58:59]
	global_store_dwordx4 v[164:165], v[110:113], off
	global_store_dwordx4 v[164:165], v[106:109], off offset:64
	global_store_dwordx4 v[164:165], v[46:49], off offset:512
	global_store_dwordx4 v[164:165], v[42:45], off offset:576
	s_mov_b64 s[56:57], 0x100000
	v_lshl_add_u64 v[162:163], v[158:159], 0, s[56:57]
	global_load_dwordx4 v[198:201], v[162:163], off nt
	global_load_dwordx4 v[202:205], v[162:163], off offset:64 nt
	global_load_dwordx4 v[206:209], v[162:163], off offset:512 nt
	global_load_dwordx4 v[210:213], v[162:163], off offset:576 nt
	s_waitcnt vmcnt(8)
;     __device__ __forceinline__ void operator()(const Acc& acc, const Unit& u, int wr, int wc, int fr, int fq) const {
;     ...
;                 for (int m = 0; m < 4; ++m)
; #pragma unroll
;                     for (int n = 0; n < 2; ++n) { const size_t off = (size_t)(u.pm * BM + ai * HALF + wr * 64 + m * 16 + fr) * DMODEL + col0 + bj * HALF + n * 16; bsv[m][n] = __builtin_nontemporal_load((const f32x4*)(base + off)); }
; #pragma unroll
;                 for (int m = 0; m < 4; ++m)
; #pragma unroll
;                     for (int n = 0; n < 2; ++n) { const size_t off = (size_t)(u.pm * BM + ai * HALF + wr * 64 + m * 16 + fr) * DMODEL + col0 + bj * HALF + n * 16;
;                         *(f32x4*)(out + off) = bsv[m][n] * ALPHA + gvv[bj][n] * acc[ai][bj][m][n]; } }
	v_pk_mul_f32 v[222:223], v[222:223], s[14:15] op_sel_hi:[1,0]
	v_pk_mul_f32 v[224:225], v[224:225], s[14:15] op_sel_hi:[1,0]
	v_pk_mul_f32 v[226:227], v[226:227], s[14:15] op_sel_hi:[1,0]
	v_pk_mul_f32 v[228:229], v[228:229], s[14:15] op_sel_hi:[1,0]
	v_pk_mul_f32 v[230:231], v[230:231], s[14:15] op_sel_hi:[1,0]
	v_pk_mul_f32 v[232:233], v[232:233], s[14:15] op_sel_hi:[1,0]
	v_pk_mul_f32 v[234:235], v[234:235], s[14:15] op_sel_hi:[1,0]
	v_pk_mul_f32 v[236:237], v[236:237], s[14:15] op_sel_hi:[1,0]
	v_pk_fma_f32 v[102:103], v[102:103], v[142:143], v[222:223]
	v_pk_fma_f32 v[104:105], v[104:105], v[144:145], v[224:225]
	v_pk_fma_f32 v[98:99], v[98:99], v[138:139], v[226:227]
	v_pk_fma_f32 v[100:101], v[100:101], v[140:141], v[228:229]
	v_pk_fma_f32 v[38:39], v[38:39], v[134:135], v[230:231]
	v_pk_fma_f32 v[40:41], v[40:41], v[136:137], v[232:233]
	v_pk_fma_f32 v[34:35], v[34:35], v[130:131], v[234:235]
	v_pk_fma_f32 v[36:37], v[36:37], v[132:133], v[236:237]
	s_mov_b64 s[58:59], 0x60000
	v_lshl_add_u64 v[164:165], v[160:161], 0, s[58:59]
	global_store_dwordx4 v[164:165], v[102:105], off
	global_store_dwordx4 v[164:165], v[98:101], off offset:64
	global_store_dwordx4 v[164:165], v[38:41], off offset:512
	global_store_dwordx4 v[164:165], v[34:37], off offset:576
	s_mov_b64 s[56:57], 0x120000
	v_lshl_add_u64 v[162:163], v[158:159], 0, s[56:57]
	global_load_dwordx4 v[222:225], v[162:163], off nt
	global_load_dwordx4 v[226:229], v[162:163], off offset:64 nt
	global_load_dwordx4 v[230:233], v[162:163], off offset:512 nt
	global_load_dwordx4 v[234:237], v[162:163], off offset:576 nt
	s_waitcnt vmcnt(8)
	v_pk_mul_f32 v[198:199], v[198:199], s[14:15] op_sel_hi:[1,0]
	v_pk_mul_f32 v[200:201], v[200:201], s[14:15] op_sel_hi:[1,0]
	v_pk_mul_f32 v[202:203], v[202:203], s[14:15] op_sel_hi:[1,0]
	v_pk_mul_f32 v[204:205], v[204:205], s[14:15] op_sel_hi:[1,0]
	v_pk_mul_f32 v[206:207], v[206:207], s[14:15] op_sel_hi:[1,0]
	v_pk_mul_f32 v[208:209], v[208:209], s[14:15] op_sel_hi:[1,0]
	v_pk_mul_f32 v[210:211], v[210:211], s[14:15] op_sel_hi:[1,0]
	v_pk_mul_f32 v[212:213], v[212:213], s[14:15] op_sel_hi:[1,0]
	v_pk_fma_f32 v[94:95], v[94:95], v[142:143], v[198:199]
	v_pk_fma_f32 v[96:97], v[96:97], v[144:145], v[200:201]
	v_pk_fma_f32 v[90:91], v[90:91], v[138:139], v[202:203]
	v_pk_fma_f32 v[92:93], v[92:93], v[140:141], v[204:205]
	v_pk_fma_f32 v[30:31], v[30:31], v[134:135], v[206:207]
	v_pk_fma_f32 v[32:33], v[32:33], v[136:137], v[208:209]
	v_pk_fma_f32 v[26:27], v[26:27], v[130:131], v[210:211]
	v_pk_fma_f32 v[28:29], v[28:29], v[132:133], v[212:213]
	s_mov_b64 s[58:59], 0x100000
	v_lshl_add_u64 v[164:165], v[160:161], 0, s[58:59]
	global_store_dwordx4 v[164:165], v[94:97], off
	global_store_dwordx4 v[164:165], v[90:93], off offset:64
	global_store_dwordx4 v[164:165], v[30:33], off offset:512
	global_store_dwordx4 v[164:165], v[26:29], off offset:576
	s_mov_b64 s[56:57], 0x140000
	v_lshl_add_u64 v[162:163], v[158:159], 0, s[56:57]
	global_load_dwordx4 v[198:201], v[162:163], off nt
	global_load_dwordx4 v[202:205], v[162:163], off offset:64 nt
	global_load_dwordx4 v[206:209], v[162:163], off offset:512 nt
	global_load_dwordx4 v[210:213], v[162:163], off offset:576 nt
	s_waitcnt vmcnt(8)
	v_pk_mul_f32 v[222:223], v[222:223], s[14:15] op_sel_hi:[1,0]
	v_pk_mul_f32 v[224:225], v[224:225], s[14:15] op_sel_hi:[1,0]
	v_pk_mul_f32 v[226:227], v[226:227], s[14:15] op_sel_hi:[1,0]
	v_pk_mul_f32 v[228:229], v[228:229], s[14:15] op_sel_hi:[1,0]
	v_pk_mul_f32 v[230:231], v[230:231], s[14:15] op_sel_hi:[1,0]
	v_pk_mul_f32 v[232:233], v[232:233], s[14:15] op_sel_hi:[1,0]
	v_pk_mul_f32 v[234:235], v[234:235], s[14:15] op_sel_hi:[1,0]
	v_pk_mul_f32 v[236:237], v[236:237], s[14:15] op_sel_hi:[1,0]
	v_pk_fma_f32 v[86:87], v[86:87], v[142:143], v[222:223]
	v_pk_fma_f32 v[88:89], v[88:89], v[144:145], v[224:225]
	v_pk_fma_f32 v[82:83], v[82:83], v[138:139], v[226:227]
	v_pk_fma_f32 v[84:85], v[84:85], v[140:141], v[228:229]
	v_pk_fma_f32 v[22:23], v[22:23], v[134:135], v[230:231]
	v_pk_fma_f32 v[24:25], v[24:25], v[136:137], v[232:233]
	v_pk_fma_f32 v[18:19], v[18:19], v[130:131], v[234:235]
	v_pk_fma_f32 v[20:21], v[20:21], v[132:133], v[236:237]
	s_mov_b64 s[58:59], 0x120000
	v_lshl_add_u64 v[164:165], v[160:161], 0, s[58:59]
	global_store_dwordx4 v[164:165], v[86:89], off
	global_store_dwordx4 v[164:165], v[82:85], off offset:64
	global_store_dwordx4 v[164:165], v[22:25], off offset:512
	global_store_dwordx4 v[164:165], v[18:21], off offset:576
	s_mov_b64 s[56:57], 0x160000
	v_lshl_add_u64 v[162:163], v[158:159], 0, s[56:57]
	global_load_dwordx4 v[222:225], v[162:163], off nt
	global_load_dwordx4 v[226:229], v[162:163], off offset:64 nt
	global_load_dwordx4 v[230:233], v[162:163], off offset:512 nt
	global_load_dwordx4 v[234:237], v[162:163], off offset:576 nt
	s_waitcnt vmcnt(8)
	v_pk_mul_f32 v[198:199], v[198:199], s[14:15] op_sel_hi:[1,0]
	v_pk_mul_f32 v[200:201], v[200:201], s[14:15] op_sel_hi:[1,0]
	v_pk_mul_f32 v[202:203], v[202:203], s[14:15] op_sel_hi:[1,0]
	v_pk_mul_f32 v[204:205], v[204:205], s[14:15] op_sel_hi:[1,0]
	v_pk_mul_f32 v[206:207], v[206:207], s[14:15] op_sel_hi:[1,0]
	v_pk_mul_f32 v[208:209], v[208:209], s[14:15] op_sel_hi:[1,0]
	v_pk_mul_f32 v[210:211], v[210:211], s[14:15] op_sel_hi:[1,0]
	v_pk_mul_f32 v[212:213], v[212:213], s[14:15] op_sel_hi:[1,0]
	v_pk_fma_f32 v[78:79], v[78:79], v[142:143], v[198:199]
	v_pk_fma_f32 v[80:81], v[80:81], v[144:145], v[200:201]
	v_pk_fma_f32 v[74:75], v[74:75], v[138:139], v[202:203]
	v_pk_fma_f32 v[76:77], v[76:77], v[140:141], v[204:205]
	v_pk_fma_f32 v[14:15], v[14:15], v[134:135], v[206:207]
	v_pk_fma_f32 v[16:17], v[16:17], v[136:137], v[208:209]
	v_pk_fma_f32 v[10:11], v[10:11], v[130:131], v[210:211]
	v_pk_fma_f32 v[12:13], v[12:13], v[132:133], v[212:213]
	s_mov_b64 s[58:59], 0x140000
	v_lshl_add_u64 v[164:165], v[160:161], 0, s[58:59]
	global_store_dwordx4 v[164:165], v[78:81], off
	global_store_dwordx4 v[164:165], v[74:77], off offset:64
	global_store_dwordx4 v[164:165], v[14:17], off offset:512
	global_store_dwordx4 v[164:165], v[10:13], off offset:576
	s_waitcnt vmcnt(4)
;     __device__ __forceinline__ void operator()(const Acc& acc, const Unit& u, int wr, int wc, int fr, int fq) const {
;     ...
;                 for (int m = 0; m < 4; ++m)
; #pragma unroll
;                     for (int n = 0; n < 2; ++n) { const size_t off = (size_t)(u.pm * BM + ai * HALF + wr * 64 + m * 16 + fr) * DMODEL + col0 + bj * HALF + n * 16;
;                         *(f32x4*)(out + off) = bsv[m][n] * ALPHA + gvv[bj][n] * acc[ai][bj][m][n]; } }
; __global__ void __launch_bounds__(512, 2) fwd_kernel(Args a) {
;     ...
;             for (int j = 0; j < 8; ++j) { sa += (va[j][0] + va[j][1]) + (va[j][2] + va[j][3]); sb += (vb[j][0] + vb[j][1]) + (vb[j][2] + vb[j][3]); }
;             const float mean_a = wave_sum(sa) * (1.0f / DMODEL), mean_b = wave_sum(sb) * (1.0f / DMODEL); float qa = 0.f, qb_ = 0.f;
	v_pk_mul_f32 v[222:223], v[222:223], s[14:15] op_sel_hi:[1,0]
	v_pk_mul_f32 v[224:225], v[224:225], s[14:15] op_sel_hi:[1,0]
	v_pk_mul_f32 v[226:227], v[226:227], s[14:15] op_sel_hi:[1,0]
	v_pk_mul_f32 v[228:229], v[228:229], s[14:15] op_sel_hi:[1,0]
	v_pk_mul_f32 v[230:231], v[230:231], s[14:15] op_sel_hi:[1,0]
	v_pk_mul_f32 v[232:233], v[232:233], s[14:15] op_sel_hi:[1,0]
	v_pk_mul_f32 v[234:235], v[234:235], s[14:15] op_sel_hi:[1,0]
	v_pk_mul_f32 v[236:237], v[236:237], s[14:15] op_sel_hi:[1,0]
	v_pk_fma_f32 v[70:71], v[70:71], v[142:143], v[222:223]
	v_pk_fma_f32 v[72:73], v[72:73], v[144:145], v[224:225]
	v_pk_fma_f32 v[66:67], v[66:67], v[138:139], v[226:227]
	v_pk_fma_f32 v[68:69], v[68:69], v[140:141], v[228:229]
	v_pk_fma_f32 v[6:7], v[6:7], v[134:135], v[230:231]
	v_pk_fma_f32 v[8:9], v[8:9], v[136:137], v[232:233]
	v_pk_fma_f32 v[2:3], v[2:3], v[130:131], v[234:235]
	v_pk_fma_f32 v[4:5], v[4:5], v[132:133], v[236:237]
	s_mov_b64 s[58:59], 0x160000
	v_lshl_add_u64 v[164:165], v[160:161], 0, s[58:59]
	global_store_dwordx4 v[164:165], v[70:73], off
	global_store_dwordx4 v[164:165], v[66:69], off offset:64
	global_store_dwordx4 v[164:165], v[6:9], off offset:512
	global_store_dwordx4 v[164:165], v[2:5], off offset:576
	v_pk_add_f32 v[198:199], v[126:127], v[128:129]
	v_pk_add_f32 v[198:199], v[198:199], v[122:123]
	v_pk_add_f32 v[198:199], v[198:199], v[124:125]
	v_pk_add_f32 v[198:199], v[198:199], v[62:63]
	v_pk_add_f32 v[198:199], v[198:199], v[64:65]
	v_pk_add_f32 v[198:199], v[198:199], v[58:59]
	v_pk_add_f32 v[198:199], v[198:199], v[60:61]
	v_add_f32_e32 v146, v198, v199
	v_pk_add_f32 v[200:201], v[118:119], v[120:121]
	v_pk_add_f32 v[200:201], v[200:201], v[114:115]
	v_pk_add_f32 v[200:201], v[200:201], v[116:117]
	v_pk_add_f32 v[200:201], v[200:201], v[54:55]
	v_pk_add_f32 v[200:201], v[200:201], v[56:57]
	v_pk_add_f32 v[200:201], v[200:201], v[50:51]
	v_pk_add_f32 v[200:201], v[200:201], v[52:53]
	v_add_f32_e32 v147, v200, v201
	v_pk_add_f32 v[202:203], v[110:111], v[112:113]
	v_pk_add_f32 v[202:203], v[202:203], v[106:107]
	v_pk_add_f32 v[202:203], v[202:203], v[108:109]
	v_pk_add_f32 v[202:203], v[202:203], v[46:47]
	v_pk_add_f32 v[202:203], v[202:203], v[48:49]
	v_pk_add_f32 v[202:203], v[202:203], v[42:43]
	v_pk_add_f32 v[202:203], v[202:203], v[44:45]
	v_add_f32_e32 v148, v202, v203
	v_pk_add_f32 v[204:205], v[102:103], v[104:105]
	v_pk_add_f32 v[204:205], v[204:205], v[98:99]
	v_pk_add_f32 v[204:205], v[204:205], v[100:101]
	v_pk_add_f32 v[204:205], v[204:205], v[38:39]
	v_pk_add_f32 v[204:205], v[204:205], v[40:41]
	v_pk_add_f32 v[204:205], v[204:205], v[34:35]
	v_pk_add_f32 v[204:205], v[204:205], v[36:37]
	v_add_f32_e32 v149, v204, v205
	v_pk_add_f32 v[198:199], v[94:95], v[96:97]
	v_pk_add_f32 v[198:199], v[198:199], v[90:91]
	v_pk_add_f32 v[198:199], v[198:199], v[92:93]
	v_pk_add_f32 v[198:199], v[198:199], v[30:31]
	v_pk_add_f32 v[198:199], v[198:199], v[32:33]
	v_pk_add_f32 v[198:199], v[198:199], v[26:27]
	v_pk_add_f32 v[198:199], v[198:199], v[28:29]
	v_add_f32_e32 v150, v198, v199
	v_pk_add_f32 v[200:201], v[86:87], v[88:89]
	v_pk_add_f32 v[200:201], v[200:201], v[82:83]
	v_pk_add_f32 v[200:201], v[200:201], v[84:85]
	v_pk_add_f32 v[200:201], v[200:201], v[22:23]
	v_pk_add_f32 v[200:201], v[200:201], v[24:25]
	v_pk_add_f32 v[200:201], v[200:201], v[18:19]
	v_pk_add_f32 v[200:201], v[200:201], v[20:21]
	v_add_f32_e32 v151, v200, v201
	v_pk_add_f32 v[202:203], v[78:79], v[80:81]
	v_pk_add_f32 v[202:203], v[202:203], v[74:75]
	v_pk_add_f32 v[202:203], v[202:203], v[76:77]
	v_pk_add_f32 v[202:203], v[202:203], v[14:15]
	v_pk_add_f32 v[202:203], v[202:203], v[16:17]
	v_pk_add_f32 v[202:203], v[202:203], v[10:11]
	v_pk_add_f32 v[202:203], v[202:203], v[12:13]
	v_add_f32_e32 v152, v202, v203
	v_pk_add_f32 v[204:205], v[70:71], v[72:73]
	v_pk_add_f32 v[204:205], v[204:205], v[66:67]
	v_pk_add_f32 v[204:205], v[204:205], v[68:69]
	v_pk_add_f32 v[204:205], v[204:205], v[6:7]
	v_pk_add_f32 v[204:205], v[204:205], v[8:9]
	v_pk_add_f32 v[204:205], v[204:205], v[2:3]
	v_pk_add_f32 v[204:205], v[204:205], v[4:5]
	v_add_f32_e32 v153, v204, v205
	v_mov_b32_e32 v238, v146
	v_mov_b32_e32 v246, v146
	v_mov_b32_e32 v239, v147
	v_mov_b32_e32 v247, v147
	v_mov_b32_e32 v240, v148
	v_mov_b32_e32 v248, v148
	v_mov_b32_e32 v241, v149
	v_mov_b32_e32 v249, v149
	v_mov_b32_e32 v242, v150
	v_mov_b32_e32 v250, v150
	v_mov_b32_e32 v243, v151
	v_mov_b32_e32 v251, v151
	v_mov_b32_e32 v244, v152
	v_mov_b32_e32 v252, v152
	v_mov_b32_e32 v245, v153
	v_mov_b32_e32 v253, v153
	s_nop 1
	v_permlane16_swap_b32_e32 v238, v246
	v_permlane16_swap_b32_e32 v239, v247
	v_permlane16_swap_b32_e32 v240, v248
	v_permlane16_swap_b32_e32 v241, v249
	v_permlane16_swap_b32_e32 v242, v250
	v_permlane16_swap_b32_e32 v243, v251
	v_permlane16_swap_b32_e32 v244, v252
	v_permlane16_swap_b32_e32 v245, v253
	s_nop 1
	v_add_f32_e32 v146, v238, v246
	v_add_f32_e32 v147, v239, v247
	v_add_f32_e32 v148, v240, v248
	v_add_f32_e32 v149, v241, v249
	v_add_f32_e32 v150, v242, v250
	v_add_f32_e32 v151, v243, v251
	v_add_f32_e32 v152, v244, v252
	v_add_f32_e32 v153, v245, v253
	v_mov_b32_e32 v238, v146
	v_mov_b32_e32 v246, v146
	v_mov_b32_e32 v239, v147
	v_mov_b32_e32 v247, v147
	v_mov_b32_e32 v240, v148
	v_mov_b32_e32 v248, v148
	v_mov_b32_e32 v241, v149
	v_mov_b32_e32 v249, v149
	v_mov_b32_e32 v242, v150
	v_mov_b32_e32 v250, v150
	v_mov_b32_e32 v243, v151
	v_mov_b32_e32 v251, v151
	v_mov_b32_e32 v244, v152
	v_mov_b32_e32 v252, v152
	v_mov_b32_e32 v245, v153
	v_mov_b32_e32 v253, v153
	s_nop 1
	v_permlane32_swap_b32_e32 v238, v246
	v_permlane32_swap_b32_e32 v239, v247
	v_permlane32_swap_b32_e32 v240, v248
	v_permlane32_swap_b32_e32 v241, v249
	v_permlane32_swap_b32_e32 v242, v250
	v_permlane32_swap_b32_e32 v243, v251
	v_permlane32_swap_b32_e32 v244, v252
	v_permlane32_swap_b32_e32 v245, v253
	s_nop 1
	v_add_f32_e32 v146, v238, v246
	v_add_f32_e32 v147, v239, v247
	v_add_f32_e32 v148, v240, v248
	v_add_f32_e32 v149, v241, v249
	v_add_f32_e32 v150, v242, v250
	v_add_f32_e32 v151, v243, v251
	v_add_f32_e32 v152, v244, v252
	v_add_f32_e32 v153, v245, v253
	s_and_b32 s56, s96, 3
	s_lshl_b32 s56, s56, 2
	v_lshl_add_u32 v214, v1, 4, s56
	v_lshlrev_b32_e32 v215, 4, v1
	s_waitcnt lgkmcnt(0)
	s_barrier
; __global__ void __launch_bounds__(512, 2) fwd_kernel(Args a) {
;     ...
;             for (int j = 0; j < 8; ++j) { sa += (va[j][0] + va[j][1]) + (va[j][2] + va[j][3]); sb += (vb[j][0] + vb[j][1]) + (vb[j][2] + vb[j][3]); }
;             const float mean_a = wave_sum(sa) * (1.0f / DMODEL), mean_b = wave_sum(sb) * (1.0f / DMODEL); float qa = 0.f, qb_ = 0.f;
; #pragma unroll
;             for (int j = 0; j < 8; ++j) { va[j] = va[j] - mean_a; vb[j] = vb[j] - mean_b;
;                 qa += (va[j][0] * va[j][0] + va[j][1] * va[j][1]) + (va[j][2] * va[j][2] + va[j][3] * va[j][3]);
;                 qb_ += (vb[j][0] * vb[j][0] + vb[j][1] * vb[j][1]) + (vb[j][2] * vb[j][2] + vb[j][3] * vb[j][3]); }
	ds_write_b32 v214, v146
	ds_write_b32 v214, v147 offset:256
	ds_write_b32 v214, v148 offset:512
	ds_write_b32 v214, v149 offset:768
	ds_write_b32 v214, v150 offset:2048
	ds_write_b32 v214, v151 offset:2304
	ds_write_b32 v214, v152 offset:2560
	ds_write_b32 v214, v153 offset:2816
	s_waitcnt lgkmcnt(0)
	s_barrier
	ds_read_b128 v[198:201], v215
	ds_read_b128 v[202:205], v215 offset:256
	ds_read_b128 v[206:209], v215 offset:512
	ds_read_b128 v[210:213], v215 offset:768
	ds_read_b128 v[222:225], v215 offset:2048
	ds_read_b128 v[226:229], v215 offset:2304
	ds_read_b128 v[230:233], v215 offset:2560
	ds_read_b128 v[234:237], v215 offset:2816
	s_waitcnt lgkmcnt(0)
	v_add_f32_e32 v130, v198, v199
	v_add_f32_e32 v130, v130, v200
	v_add_f32_e32 v130, v130, v201
	v_mul_f32_e32 v178, 0x3b800000, v130
	v_add_f32_e32 v132, v202, v203
	v_add_f32_e32 v132, v132, v204
	v_add_f32_e32 v132, v132, v205
	v_mul_f32_e32 v180, 0x3b800000, v132
	v_add_f32_e32 v134, v206, v207
	v_add_f32_e32 v134, v134, v208
	v_add_f32_e32 v134, v134, v209
	v_mul_f32_e32 v182, 0x3b800000, v134
	v_add_f32_e32 v136, v210, v211
	v_add_f32_e32 v136, v136, v212
	v_add_f32_e32 v136, v136, v213
	v_mul_f32_e32 v184, 0x3b800000, v136
	v_add_f32_e32 v138, v222, v223
	v_add_f32_e32 v138, v138, v224
	v_add_f32_e32 v138, v138, v225
	v_mul_f32_e32 v186, 0x3b800000, v138
	v_add_f32_e32 v140, v226, v227
	v_add_f32_e32 v140, v140, v228
	v_add_f32_e32 v140, v140, v229
	v_mul_f32_e32 v188, 0x3b800000, v140
	v_add_f32_e32 v142, v230, v231
	v_add_f32_e32 v142, v142, v232
	v_add_f32_e32 v142, v142, v233
	v_mul_f32_e32 v190, 0x3b800000, v142
	v_add_f32_e32 v144, v234, v235
	v_add_f32_e32 v144, v144, v236
	v_add_f32_e32 v144, v144, v237
	v_mul_f32_e32 v192, 0x3b800000, v144
	v_pk_add_f32 v[200:201], v[126:127], v[178:179] op_sel_hi:[1,0] neg_lo:[0,1] neg_hi:[0,1]
	v_pk_mul_f32 v[198:199], v[200:201], v[200:201]
	v_pk_add_f32 v[200:201], v[128:129], v[178:179] op_sel_hi:[1,0] neg_lo:[0,1] neg_hi:[0,1]
	v_pk_fma_f32 v[198:199], v[200:201], v[200:201], v[198:199]
	v_pk_add_f32 v[200:201], v[122:123], v[178:179] op_sel_hi:[1,0] neg_lo:[0,1] neg_hi:[0,1]
	v_pk_fma_f32 v[198:199], v[200:201], v[200:201], v[198:199]
	v_pk_add_f32 v[200:201], v[124:125], v[178:179] op_sel_hi:[1,0] neg_lo:[0,1] neg_hi:[0,1]
	v_pk_fma_f32 v[198:199], v[200:201], v[200:201], v[198:199]
	v_pk_add_f32 v[200:201], v[62:63], v[178:179] op_sel_hi:[1,0] neg_lo:[0,1] neg_hi:[0,1]
	v_pk_fma_f32 v[198:199], v[200:201], v[200:201], v[198:199]
	v_pk_add_f32 v[200:201], v[64:65], v[178:179] op_sel_hi:[1,0] neg_lo:[0,1] neg_hi:[0,1]
	v_pk_fma_f32 v[198:199], v[200:201], v[200:201], v[198:199]
	v_pk_add_f32 v[200:201], v[58:59], v[178:179] op_sel_hi:[1,0] neg_lo:[0,1] neg_hi:[0,1]
	v_pk_fma_f32 v[198:199], v[200:201], v[200:201], v[198:199]
	v_pk_add_f32 v[200:201], v[60:61], v[178:179] op_sel_hi:[1,0] neg_lo:[0,1] neg_hi:[0,1]
	v_pk_fma_f32 v[198:199], v[200:201], v[200:201], v[198:199]
	v_add_f32_e32 v146, v198, v199
	v_pk_add_f32 v[204:205], v[118:119], v[180:181] op_sel_hi:[1,0] neg_lo:[0,1] neg_hi:[0,1]
	v_pk_mul_f32 v[202:203], v[204:205], v[204:205]
	v_pk_add_f32 v[204:205], v[120:121], v[180:181] op_sel_hi:[1,0] neg_lo:[0,1] neg_hi:[0,1]
	v_pk_fma_f32 v[202:203], v[204:205], v[204:205], v[202:203]
	v_pk_add_f32 v[204:205], v[114:115], v[180:181] op_sel_hi:[1,0] neg_lo:[0,1] neg_hi:[0,1]
	v_pk_fma_f32 v[202:203], v[204:205], v[204:205], v[202:203]
	v_pk_add_f32 v[204:205], v[116:117], v[180:181] op_sel_hi:[1,0] neg_lo:[0,1] neg_hi:[0,1]
	v_pk_fma_f32 v[202:203], v[204:205], v[204:205], v[202:203]
	v_pk_add_f32 v[204:205], v[54:55], v[180:181] op_sel_hi:[1,0] neg_lo:[0,1] neg_hi:[0,1]
	v_pk_fma_f32 v[202:203], v[204:205], v[204:205], v[202:203]
	v_pk_add_f32 v[204:205], v[56:57], v[180:181] op_sel_hi:[1,0] neg_lo:[0,1] neg_hi:[0,1]
	v_pk_fma_f32 v[202:203], v[204:205], v[204:205], v[202:203]
	v_pk_add_f32 v[204:205], v[50:51], v[180:181] op_sel_hi:[1,0] neg_lo:[0,1] neg_hi:[0,1]
	v_pk_fma_f32 v[202:203], v[204:205], v[204:205], v[202:203]
	v_pk_add_f32 v[204:205], v[52:53], v[180:181] op_sel_hi:[1,0] neg_lo:[0,1] neg_hi:[0,1]
	v_pk_fma_f32 v[202:203], v[204:205], v[204:205], v[202:203]
	v_add_f32_e32 v147, v202, v203
	v_pk_add_f32 v[208:209], v[110:111], v[182:183] op_sel_hi:[1,0] neg_lo:[0,1] neg_hi:[0,1]
	v_pk_mul_f32 v[206:207], v[208:209], v[208:209]
	v_pk_add_f32 v[208:209], v[112:113], v[182:183] op_sel_hi:[1,0] neg_lo:[0,1] neg_hi:[0,1]
	v_pk_fma_f32 v[206:207], v[208:209], v[208:209], v[206:207]
	v_pk_add_f32 v[208:209], v[106:107], v[182:183] op_sel_hi:[1,0] neg_lo:[0,1] neg_hi:[0,1]
	v_pk_fma_f32 v[206:207], v[208:209], v[208:209], v[206:207]
	v_pk_add_f32 v[208:209], v[108:109], v[182:183] op_sel_hi:[1,0] neg_lo:[0,1] neg_hi:[0,1]
	v_pk_fma_f32 v[206:207], v[208:209], v[208:209], v[206:207]
	v_pk_add_f32 v[208:209], v[46:47], v[182:183] op_sel_hi:[1,0] neg_lo:[0,1] neg_hi:[0,1]
	v_pk_fma_f32 v[206:207], v[208:209], v[208:209], v[206:207]
	v_pk_add_f32 v[208:209], v[48:49], v[182:183] op_sel_hi:[1,0] neg_lo:[0,1] neg_hi:[0,1]
	v_pk_fma_f32 v[206:207], v[208:209], v[208:209], v[206:207]
	v_pk_add_f32 v[208:209], v[42:43], v[182:183] op_sel_hi:[1,0] neg_lo:[0,1] neg_hi:[0,1]
	v_pk_fma_f32 v[206:207], v[208:209], v[208:209], v[206:207]
	v_pk_add_f32 v[208:209], v[44:45], v[182:183] op_sel_hi:[1,0] neg_lo:[0,1] neg_hi:[0,1]
	v_pk_fma_f32 v[206:207], v[208:209], v[208:209], v[206:207]
	v_add_f32_e32 v148, v206, v207
	v_pk_add_f32 v[212:213], v[102:103], v[184:185] op_sel_hi:[1,0] neg_lo:[0,1] neg_hi:[0,1]
	v_pk_mul_f32 v[210:211], v[212:213], v[212:213]
	v_pk_add_f32 v[212:213], v[104:105], v[184:185] op_sel_hi:[1,0] neg_lo:[0,1] neg_hi:[0,1]
; __global__ void __launch_bounds__(512, 2) fwd_kernel(Args a) {
;     ...
;             for (int j = 0; j < 8; ++j) { va[j] = va[j] - mean_a; vb[j] = vb[j] - mean_b;
;                 qa += (va[j][0] * va[j][0] + va[j][1] * va[j][1]) + (va[j][2] * va[j][2] + va[j][3] * va[j][3]);
;                 qb_ += (vb[j][0] * vb[j][0] + vb[j][1] * vb[j][1]) + (vb[j][2] * vb[j][2] + vb[j][3] * vb[j][3]); }
	v_pk_fma_f32 v[210:211], v[212:213], v[212:213], v[210:211]
	v_pk_add_f32 v[212:213], v[98:99], v[184:185] op_sel_hi:[1,0] neg_lo:[0,1] neg_hi:[0,1]
	v_pk_fma_f32 v[210:211], v[212:213], v[212:213], v[210:211]
	v_pk_add_f32 v[212:213], v[100:101], v[184:185] op_sel_hi:[1,0] neg_lo:[0,1] neg_hi:[0,1]
	v_pk_fma_f32 v[210:211], v[212:213], v[212:213], v[210:211]
	v_pk_add_f32 v[212:213], v[38:39], v[184:185] op_sel_hi:[1,0] neg_lo:[0,1] neg_hi:[0,1]
	v_pk_fma_f32 v[210:211], v[212:213], v[212:213], v[210:211]
	v_pk_add_f32 v[212:213], v[40:41], v[184:185] op_sel_hi:[1,0] neg_lo:[0,1] neg_hi:[0,1]
	v_pk_fma_f32 v[210:211], v[212:213], v[212:213], v[210:211]
	v_pk_add_f32 v[212:213], v[34:35], v[184:185] op_sel_hi:[1,0] neg_lo:[0,1] neg_hi:[0,1]
	v_pk_fma_f32 v[210:211], v[212:213], v[212:213], v[210:211]
	v_pk_add_f32 v[212:213], v[36:37], v[184:185] op_sel_hi:[1,0] neg_lo:[0,1] neg_hi:[0,1]
	v_pk_fma_f32 v[210:211], v[212:213], v[212:213], v[210:211]
	v_add_f32_e32 v149, v210, v211
	v_pk_add_f32 v[200:201], v[94:95], v[186:187] op_sel_hi:[1,0] neg_lo:[0,1] neg_hi:[0,1]
	v_pk_mul_f32 v[198:199], v[200:201], v[200:201]
	v_pk_add_f32 v[200:201], v[96:97], v[186:187] op_sel_hi:[1,0] neg_lo:[0,1] neg_hi:[0,1]
	v_pk_fma_f32 v[198:199], v[200:201], v[200:201], v[198:199]
	v_pk_add_f32 v[200:201], v[90:91], v[186:187] op_sel_hi:[1,0] neg_lo:[0,1] neg_hi:[0,1]
	v_pk_fma_f32 v[198:199], v[200:201], v[200:201], v[198:199]
	v_pk_add_f32 v[200:201], v[92:93], v[186:187] op_sel_hi:[1,0] neg_lo:[0,1] neg_hi:[0,1]
	v_pk_fma_f32 v[198:199], v[200:201], v[200:201], v[198:199]
	v_pk_add_f32 v[200:201], v[30:31], v[186:187] op_sel_hi:[1,0] neg_lo:[0,1] neg_hi:[0,1]
	v_pk_fma_f32 v[198:199], v[200:201], v[200:201], v[198:199]
	v_pk_add_f32 v[200:201], v[32:33], v[186:187] op_sel_hi:[1,0] neg_lo:[0,1] neg_hi:[0,1]
	v_pk_fma_f32 v[198:199], v[200:201], v[200:201], v[198:199]
	v_pk_add_f32 v[200:201], v[26:27], v[186:187] op_sel_hi:[1,0] neg_lo:[0,1] neg_hi:[0,1]
	v_pk_fma_f32 v[198:199], v[200:201], v[200:201], v[198:199]
	v_pk_add_f32 v[200:201], v[28:29], v[186:187] op_sel_hi:[1,0] neg_lo:[0,1] neg_hi:[0,1]
	v_pk_fma_f32 v[198:199], v[200:201], v[200:201], v[198:199]
	v_add_f32_e32 v150, v198, v199
	v_pk_add_f32 v[204:205], v[86:87], v[188:189] op_sel_hi:[1,0] neg_lo:[0,1] neg_hi:[0,1]
	v_pk_mul_f32 v[202:203], v[204:205], v[204:205]
	v_pk_add_f32 v[204:205], v[88:89], v[188:189] op_sel_hi:[1,0] neg_lo:[0,1] neg_hi:[0,1]
	v_pk_fma_f32 v[202:203], v[204:205], v[204:205], v[202:203]
	v_pk_add_f32 v[204:205], v[82:83], v[188:189] op_sel_hi:[1,0] neg_lo:[0,1] neg_hi:[0,1]
	v_pk_fma_f32 v[202:203], v[204:205], v[204:205], v[202:203]
	v_pk_add_f32 v[204:205], v[84:85], v[188:189] op_sel_hi:[1,0] neg_lo:[0,1] neg_hi:[0,1]
	v_pk_fma_f32 v[202:203], v[204:205], v[204:205], v[202:203]
	v_pk_add_f32 v[204:205], v[22:23], v[188:189] op_sel_hi:[1,0] neg_lo:[0,1] neg_hi:[0,1]
	v_pk_fma_f32 v[202:203], v[204:205], v[204:205], v[202:203]
	v_pk_add_f32 v[204:205], v[24:25], v[188:189] op_sel_hi:[1,0] neg_lo:[0,1] neg_hi:[0,1]
	v_pk_fma_f32 v[202:203], v[204:205], v[204:205], v[202:203]
	v_pk_add_f32 v[204:205], v[18:19], v[188:189] op_sel_hi:[1,0] neg_lo:[0,1] neg_hi:[0,1]
	v_pk_fma_f32 v[202:203], v[204:205], v[204:205], v[202:203]
	v_pk_add_f32 v[204:205], v[20:21], v[188:189] op_sel_hi:[1,0] neg_lo:[0,1] neg_hi:[0,1]
	v_pk_fma_f32 v[202:203], v[204:205], v[204:205], v[202:203]
	v_add_f32_e32 v151, v202, v203
	v_pk_add_f32 v[208:209], v[78:79], v[190:191] op_sel_hi:[1,0] neg_lo:[0,1] neg_hi:[0,1]
	v_pk_mul_f32 v[206:207], v[208:209], v[208:209]
	v_pk_add_f32 v[208:209], v[80:81], v[190:191] op_sel_hi:[1,0] neg_lo:[0,1] neg_hi:[0,1]
	v_pk_fma_f32 v[206:207], v[208:209], v[208:209], v[206:207]
	v_pk_add_f32 v[208:209], v[74:75], v[190:191] op_sel_hi:[1,0] neg_lo:[0,1] neg_hi:[0,1]
	v_pk_fma_f32 v[206:207], v[208:209], v[208:209], v[206:207]
	v_pk_add_f32 v[208:209], v[76:77], v[190:191] op_sel_hi:[1,0] neg_lo:[0,1] neg_hi:[0,1]
	v_pk_fma_f32 v[206:207], v[208:209], v[208:209], v[206:207]
	v_pk_add_f32 v[208:209], v[14:15], v[190:191] op_sel_hi:[1,0] neg_lo:[0,1] neg_hi:[0,1]
	v_pk_fma_f32 v[206:207], v[208:209], v[208:209], v[206:207]
	v_pk_add_f32 v[208:209], v[16:17], v[190:191] op_sel_hi:[1,0] neg_lo:[0,1] neg_hi:[0,1]
	v_pk_fma_f32 v[206:207], v[208:209], v[208:209], v[206:207]
	v_pk_add_f32 v[208:209], v[10:11], v[190:191] op_sel_hi:[1,0] neg_lo:[0,1] neg_hi:[0,1]
	v_pk_fma_f32 v[206:207], v[208:209], v[208:209], v[206:207]
	v_pk_add_f32 v[208:209], v[12:13], v[190:191] op_sel_hi:[1,0] neg_lo:[0,1] neg_hi:[0,1]
	v_pk_fma_f32 v[206:207], v[208:209], v[208:209], v[206:207]
	v_add_f32_e32 v152, v206, v207
	v_pk_add_f32 v[212:213], v[70:71], v[192:193] op_sel_hi:[1,0] neg_lo:[0,1] neg_hi:[0,1]
	v_pk_mul_f32 v[210:211], v[212:213], v[212:213]
	v_pk_add_f32 v[212:213], v[72:73], v[192:193] op_sel_hi:[1,0] neg_lo:[0,1] neg_hi:[0,1]
	v_pk_fma_f32 v[210:211], v[212:213], v[212:213], v[210:211]
	v_pk_add_f32 v[212:213], v[66:67], v[192:193] op_sel_hi:[1,0] neg_lo:[0,1] neg_hi:[0,1]
	v_pk_fma_f32 v[210:211], v[212:213], v[212:213], v[210:211]
	v_pk_add_f32 v[212:213], v[68:69], v[192:193] op_sel_hi:[1,0] neg_lo:[0,1] neg_hi:[0,1]
	v_pk_fma_f32 v[210:211], v[212:213], v[212:213], v[210:211]
	v_pk_add_f32 v[212:213], v[6:7], v[192:193] op_sel_hi:[1,0] neg_lo:[0,1] neg_hi:[0,1]
	v_pk_fma_f32 v[210:211], v[212:213], v[212:213], v[210:211]
; __global__ void __launch_bounds__(512, 2) fwd_kernel(Args a) {
;     ...
;             for (int j = 0; j < 8; ++j) { va[j] = va[j] - mean_a; vb[j] = vb[j] - mean_b;
;                 qa += (va[j][0] * va[j][0] + va[j][1] * va[j][1]) + (va[j][2] * va[j][2] + va[j][3] * va[j][3]);
;                 qb_ += (vb[j][0] * vb[j][0] + vb[j][1] * vb[j][1]) + (vb[j][2] * vb[j][2] + vb[j][3] * vb[j][3]); }
;             const float rstd_a = 1.0f / sqrtf(wave_sum(qa) * (1.0f / DMODEL) + LN_EPS), rstd_b = 1.0f / sqrtf(wave_sum(qb_) * (1.0f / DMODEL) + LN_EPS);
	v_pk_add_f32 v[212:213], v[8:9], v[192:193] op_sel_hi:[1,0] neg_lo:[0,1] neg_hi:[0,1]
	v_pk_fma_f32 v[210:211], v[212:213], v[212:213], v[210:211]
	v_pk_add_f32 v[212:213], v[2:3], v[192:193] op_sel_hi:[1,0] neg_lo:[0,1] neg_hi:[0,1]
	v_pk_fma_f32 v[210:211], v[212:213], v[212:213], v[210:211]
	v_pk_add_f32 v[212:213], v[4:5], v[192:193] op_sel_hi:[1,0] neg_lo:[0,1] neg_hi:[0,1]
	v_pk_fma_f32 v[210:211], v[212:213], v[212:213], v[210:211]
	v_add_f32_e32 v153, v210, v211
	v_mov_b32_e32 v238, v146
	v_mov_b32_e32 v246, v146
	v_mov_b32_e32 v239, v147
	v_mov_b32_e32 v247, v147
	v_mov_b32_e32 v240, v148
	v_mov_b32_e32 v248, v148
	v_mov_b32_e32 v241, v149
	v_mov_b32_e32 v249, v149
	v_mov_b32_e32 v242, v150
	v_mov_b32_e32 v250, v150
	v_mov_b32_e32 v243, v151
	v_mov_b32_e32 v251, v151
	v_mov_b32_e32 v244, v152
	v_mov_b32_e32 v252, v152
	v_mov_b32_e32 v245, v153
	v_mov_b32_e32 v253, v153
	s_nop 1
	v_permlane16_swap_b32_e32 v238, v246
	v_permlane16_swap_b32_e32 v239, v247
	v_permlane16_swap_b32_e32 v240, v248
	v_permlane16_swap_b32_e32 v241, v249
	v_permlane16_swap_b32_e32 v242, v250
	v_permlane16_swap_b32_e32 v243, v251
	v_permlane16_swap_b32_e32 v244, v252
	v_permlane16_swap_b32_e32 v245, v253
	s_nop 1
	v_add_f32_e32 v146, v238, v246
	v_add_f32_e32 v147, v239, v247
	v_add_f32_e32 v148, v240, v248
	v_add_f32_e32 v149, v241, v249
	v_add_f32_e32 v150, v242, v250
	v_add_f32_e32 v151, v243, v251
	v_add_f32_e32 v152, v244, v252
	v_add_f32_e32 v153, v245, v253
	v_mov_b32_e32 v238, v146
	v_mov_b32_e32 v246, v146
	v_mov_b32_e32 v239, v147
	v_mov_b32_e32 v247, v147
	v_mov_b32_e32 v240, v148
	v_mov_b32_e32 v248, v148
	v_mov_b32_e32 v241, v149
	v_mov_b32_e32 v249, v149
	v_mov_b32_e32 v242, v150
	v_mov_b32_e32 v250, v150
	v_mov_b32_e32 v243, v151
	v_mov_b32_e32 v251, v151
	v_mov_b32_e32 v244, v152
	v_mov_b32_e32 v252, v152
	v_mov_b32_e32 v245, v153
	v_mov_b32_e32 v253, v153
	s_nop 1
	v_permlane32_swap_b32_e32 v238, v246
	v_permlane32_swap_b32_e32 v239, v247
	v_permlane32_swap_b32_e32 v240, v248
	v_permlane32_swap_b32_e32 v241, v249
	v_permlane32_swap_b32_e32 v242, v250
	v_permlane32_swap_b32_e32 v243, v251
	v_permlane32_swap_b32_e32 v244, v252
	v_permlane32_swap_b32_e32 v245, v253
	s_nop 1
	v_add_f32_e32 v146, v238, v246
	v_add_f32_e32 v147, v239, v247
	v_add_f32_e32 v148, v240, v248
	v_add_f32_e32 v149, v241, v249
	v_add_f32_e32 v150, v242, v250
	v_add_f32_e32 v151, v243, v251
	v_add_f32_e32 v152, v244, v252
	v_add_f32_e32 v153, v245, v253
	ds_write_b32 v214, v146 offset:4096
	ds_write_b32 v214, v147 offset:4352
	ds_write_b32 v214, v148 offset:4608
	ds_write_b32 v214, v149 offset:4864
	ds_write_b32 v214, v150 offset:6144
	ds_write_b32 v214, v151 offset:6400
	ds_write_b32 v214, v152 offset:6656
	ds_write_b32 v214, v153 offset:6912
	s_waitcnt lgkmcnt(0)
	s_barrier
	ds_read_b128 v[198:201], v215 offset:4096
	ds_read_b128 v[202:205], v215 offset:4352
	ds_read_b128 v[206:209], v215 offset:4608
	ds_read_b128 v[210:213], v215 offset:4864
	ds_read_b128 v[222:225], v215 offset:6144
	ds_read_b128 v[226:229], v215 offset:6400
	ds_read_b128 v[230:233], v215 offset:6656
	ds_read_b128 v[234:237], v215 offset:6912
	s_waitcnt lgkmcnt(0)
	v_add_f32_e32 v131, v198, v199
	v_add_f32_e32 v131, v131, v200
	v_add_f32_e32 v131, v131, v201
	v_add_f32_e32 v133, v202, v203
	v_add_f32_e32 v133, v133, v204
	v_add_f32_e32 v133, v133, v205
	v_add_f32_e32 v135, v206, v207
	v_add_f32_e32 v135, v135, v208
	v_add_f32_e32 v135, v135, v209
	v_add_f32_e32 v137, v210, v211
	v_add_f32_e32 v137, v137, v212
	v_add_f32_e32 v137, v137, v213
	v_add_f32_e32 v139, v222, v223
	v_add_f32_e32 v139, v139, v224
	v_add_f32_e32 v139, v139, v225
	v_add_f32_e32 v141, v226, v227
	v_add_f32_e32 v141, v141, v228
	v_add_f32_e32 v141, v141, v229
	v_add_f32_e32 v143, v230, v231
	v_add_f32_e32 v143, v143, v232
	v_add_f32_e32 v143, v143, v233
	v_add_f32_e32 v145, v234, v235
	v_add_f32_e32 v145, v145, v236
	v_add_f32_e32 v145, v145, v237
	s_and_b32 s56, s96, 3
	s_cmp_lg_u32 s56, 0
	s_cbranch_scc1 .Lln1_nostat
	s_mov_b64 s[58:59], exec
	s_mov_b64 exec, 0xffff
	v_lshlrev_b32_e32 v216, 6, v194
	v_lshrrev_b32_e32 v217, 10, v174
	v_lshl_add_u32 v216, v217, 3, v216
	v_add_u32_e32 v217, 0x0, v216
	global_store_dwordx2 v217, v[130:131], s[60:61]
	v_add_u32_e32 v217, 0x400, v216
	global_store_dwordx2 v217, v[132:133], s[60:61]
	v_add_u32_e32 v217, 0x800, v216
	global_store_dwordx2 v217, v[134:135], s[60:61]
	v_add_u32_e32 v217, 0xc00, v216
	global_store_dwordx2 v217, v[136:137], s[60:61]
	v_add_u32_e32 v217, 0x2000, v216
	global_store_dwordx2 v217, v[138:139], s[60:61]
	v_add_u32_e32 v217, 0x2400, v216
	global_store_dwordx2 v217, v[140:141], s[60:61]
	v_add_u32_e32 v217, 0x2800, v216
	global_store_dwordx2 v217, v[142:143], s[60:61]
	v_add_u32_e32 v217, 0x2c00, v216
	global_store_dwordx2 v217, v[144:145], s[60:61]
	s_mov_b64 exec, s[58:59]
.Lln1_nostat:
	s_nop 1
	v_mov_b32_e32 v198, v2
	v_mov_b32_e32 v199, v3
	v_mov_b32_e32 v200, v4
	v_mov_b32_e32 v201, v5
	v_mov_b32_e32 v202, v6
	v_mov_b32_e32 v203, v7
	v_mov_b32_e32 v204, v8
	v_mov_b32_e32 v205, v9
	v_mov_b32_e32 v206, v10
	v_mov_b32_e32 v207, v11
	v_mov_b32_e32 v208, v12
	v_mov_b32_e32 v209, v13
	v_mov_b32_e32 v210, v14
	v_mov_b32_e32 v211, v15
	v_mov_b32_e32 v212, v16
	v_mov_b32_e32 v213, v17
	s_andn2_b64 vcc, exec, s[2:3]
	s_mov_b64 s[2:3], -1
	s_cbranch_vccnz .LBB0_895
	s_andn2_b64 vcc, exec, s[8:9]
	s_cbranch_vccnz .LBB0_894
	s_barrier
	s_branch .LBB0_894

; __global__ void __launch_bounds__(512, 2) fwd_kernel(Args a) {
;     ...
;     if (IN(9)) for (int rep = 0; rep < REPS(9); ++rep) { DECL_WS();
;         const float* const lng_p = IN_ln1_g; const float* const lnb_p = IN_ln1_b;
;         for (int m = 2 * gw; m < MTOK; m += 2 * NGW) {
;             const float* md = mod + (size_t)(m >> 12) * NADA; f32x4* xr = (f32x4*)(out + (size_t)m * DMODEL) + lane;
;             f32x4 va[8], vb[8]; float sa = 0.f, sb = 0.f;
; #pragma unroll
;             for (int j = 0; j < 8; ++j) { va[j] = __builtin_nontemporal_load(xr + 64 * j); vb[j] = __builtin_nontemporal_load(xr + 512 + 64 * j); }
; #pragma unroll
;             for (int j = 0; j < 8; ++j) { sa += (va[j][0] + va[j][1]) + (va[j][2] + va[j][3]); sb += (vb[j][0] + vb[j][1]) + (vb[j][2] + vb[j][3]); }
;             const float mean_a = wave_sum(sa) * (1.0f / DMODEL), mean_b = wave_sum(sb) * (1.0f / DMODEL); float qa = 0.f, qb_ = 0.f;
; #pragma unroll
;             for (int j = 0; j < 8; ++j) { va[j] = va[j] - mean_a; vb[j] = vb[j] - mean_b;
;                 qa += (va[j][0] * va[j][0] + va[j][1] * va[j][1]) + (va[j][2] * va[j][2] + va[j][3] * va[j][3]);
;                 qb_ += (vb[j][0] * vb[j][0] + vb[j][1] * vb[j][1]) + (vb[j][2] * vb[j][2] + vb[j][3] * vb[j][3]); }
;             const float rstd_a = 1.0f / sqrtf(wave_sum(qa) * (1.0f / DMODEL) + LN_EPS), rstd_b = 1.0f / sqrtf(wave_sum(qb_) * (1.0f / DMODEL) + LN_EPS);
;             u32x2* o8 = (u32x2*)(ubuf + (size_t)m * DMODEL) + lane;
;             f32x4 ggv[8], bbv[8], shv[8], scv[8];
; #pragma unroll
;             for (int j = 0; j < 8; ++j) { const int col = 4 * lane + 256 * j; ggv[j] = *(const f32x4*)(lng_p + col); bbv[j] = *(const f32x4*)(lnb_p + col);
;                 shv[j] = *(const f32x4*)(md + 3 * DMODEL + col); scv[j] = *(const f32x4*)(md + 4 * DMODEL + col); }
.LBB0_960:
	s_cmp_lt_i32 s90, 10
	s_cselect_b64 s[0:1], -1, 0
	s_and_b64 s[4:5], s[0:1], s[2:3]
	s_andn2_b64 vcc, exec, s[4:5]
	s_cbranch_vccnz .LBB0_964
	s_add_i32 s0, 0, 0x22098
	v_mov_b32_e32 v1, s0
	s_add_i32 s0, 0, 0x22068
	ds_read2_b64 v[2:5], v1 offset1:1
	v_mov_b32_e32 v1, s0
	ds_read2_b64 v[6:9], v1 offset1:1
	s_cmpk_gt_i32 s96, 0xfff
	s_waitcnt lgkmcnt(0)
	v_readfirstlane_b32 s7, v4
	v_readfirstlane_b32 s10, v5
	v_readfirstlane_b32 s12, v2
	v_readfirstlane_b32 s13, v3
	v_readfirstlane_b32 s0, v6
	v_readfirstlane_b32 s1, v7
	v_readfirstlane_b32 s2, v8
	v_readfirstlane_b32 s3, v9
	s_cbranch_scc1 .LBB0_964
	v_mov_b32_e32 v16, v174
	v_mov_b32_e32 v17, v194
	s_mov_b32 s6, s7
	s_mov_b32 s7, s10
	s_add_u32 s8, s6, 0x2a0000
	s_addc_u32 s9, s7, 0
	s_add_u32 s10, s6, 0x210000
	s_addc_u32 s11, s7, 0
	v_readfirstlane_b32 s14, v194
	s_lshr_b32 s14, s14, 12
	s_mul_i32 s14, s14, 0xc000
	s_add_u32 s12, s6, 0x100000
	s_addc_u32 s13, s7, 0
	s_add_u32 s12, s12, s14
	s_addc_u32 s13, s13, 0
	s_add_u32 s18, s12, 0x6000
	s_addc_u32 s19, s13, 0
	s_add_u32 s20, s12, 0x8000
	s_addc_u32 s21, s13, 0
	s_add_u32 s16, s6, 0xfc00000
	s_addc_u32 s17, s7, 0
	s_mov_b32 s15, 0xf800000
	s_mov_b32 s22, 0x3b800000
	global_load_dwordx4 v[130:133], v16, s[0:1]
	global_load_dwordx4 v[146:149], v16, s[2:3]
	global_load_dwordx4 v[162:165], v16, s[18:19]
	global_load_dwordx4 v[178:181], v16, s[20:21]
	global_load_dwordx4 v[134:137], v16, s[0:1] offset:64
	global_load_dwordx4 v[150:153], v16, s[2:3] offset:64
	global_load_dwordx4 v[166:169], v16, s[18:19] offset:64
	global_load_dwordx4 v[182:185], v16, s[20:21] offset:64
	global_load_dwordx4 v[138:141], v16, s[0:1] offset:512
	global_load_dwordx4 v[154:157], v16, s[2:3] offset:512
	global_load_dwordx4 v[170:173], v16, s[18:19] offset:512
	global_load_dwordx4 v[186:189], v16, s[20:21] offset:512
	global_load_dwordx4 v[142:145], v16, s[0:1] offset:576
	global_load_dwordx4 v[158:161], v16, s[2:3] offset:576
	global_load_dwordx4 v[174:177], v16, s[18:19] offset:576
	global_load_dwordx4 v[190:193], v16, s[20:21] offset:576
	v_lshlrev_b32_e32 v12, 12, v17
	v_mov_b32_e32 v13, 0
	v_lshl_add_u64 v[246:247], s[16:17], 0, v[12:13]
	v_lshrrev_b32_e32 v12, 1, v16
	v_lshl_add_u64 v[246:247], v[246:247], 0, v[12:13]
	v_lshlrev_b32_e32 v248, 6, v17
	v_lshlrev_b32_e32 v249, 3, v17
	v_mov_b32_e32 v250, 0x3727c5ac
	v_mov_b32_e32 v251, 0x260
	v_mov_b32_e32 v11, 0xba000000
	v_readfirstlane_b32 s23, v16
	s_lshr_b32 s23, s23, 10
	s_and_b32 s24, s96, 3
	s_or_b32 s23, s23, s24
	v_add_u32_e32 v252, 0x0, v248
	global_load_dwordx4 v[214:217], v252, s[8:9]
	global_load_dwordx4 v[218:221], v252, s[8:9] offset:16
	global_load_dwordx4 v[222:225], v252, s[8:9] offset:32
	global_load_dwordx4 v[226:229], v252, s[8:9] offset:48
	v_add_u32_e32 v252, 0x400, v248
	global_load_dwordx4 v[230:233], v252, s[8:9]
	global_load_dwordx4 v[234:237], v252, s[8:9] offset:16
	global_load_dwordx4 v[238:241], v252, s[8:9] offset:32
	global_load_dwordx4 v[242:245], v252, s[8:9] offset:48
	s_waitcnt vmcnt(8)
	v_pk_add_f32 v[178:179], v[178:179], 1.0 op_sel_hi:[1,0]
	v_pk_add_f32 v[180:181], v[180:181], 1.0 op_sel_hi:[1,0]
	v_pk_add_f32 v[182:183], v[182:183], 1.0 op_sel_hi:[1,0]
	v_pk_add_f32 v[184:185], v[184:185], 1.0 op_sel_hi:[1,0]
	v_pk_add_f32 v[186:187], v[186:187], 1.0 op_sel_hi:[1,0]
	v_pk_add_f32 v[188:189], v[188:189], 1.0 op_sel_hi:[1,0]
	v_pk_add_f32 v[190:191], v[190:191], 1.0 op_sel_hi:[1,0]
	v_pk_add_f32 v[192:193], v[192:193], 1.0 op_sel_hi:[1,0]
	s_waitcnt vmcnt(4)
	v_add_f32_e32 v8, v214, v216
	v_add_f32_e32 v8, v8, v218
	v_add_f32_e32 v8, v8, v220
	v_add_f32_e32 v8, v8, v222
	v_add_f32_e32 v8, v8, v224
	v_add_f32_e32 v8, v8, v226
	v_add_f32_e32 v8, v8, v228
	v_mul_f32_e32 v14, 0x3a000000, v8
	v_add_f32_e32 v9, v215, v217
	v_add_f32_e32 v9, v9, v219
	v_add_f32_e32 v9, v9, v221
	v_add_f32_e32 v9, v9, v223
	v_add_f32_e32 v9, v9, v225
	v_add_f32_e32 v9, v9, v227
	v_add_f32_e32 v9, v9, v229
	v_fma_f32 v15, v214, s22, -v14
	v_mul_f32_e32 v15, v15, v15
	v_fmac_f32_e32 v9, 0x43800000, v15
	v_fma_f32 v15, v216, s22, -v14
	v_mul_f32_e32 v15, v15, v15
	v_fmac_f32_e32 v9, 0x43800000, v15
	v_fma_f32 v15, v218, s22, -v14
	v_mul_f32_e32 v15, v15, v15
	v_fmac_f32_e32 v9, 0x43800000, v15
	v_fma_f32 v15, v220, s22, -v14
	v_mul_f32_e32 v15, v15, v15
	v_fmac_f32_e32 v9, 0x43800000, v15
	v_fma_f32 v15, v222, s22, -v14
	v_mul_f32_e32 v15, v15, v15
	v_fmac_f32_e32 v9, 0x43800000, v15
	v_fma_f32 v15, v224, s22, -v14
	v_mul_f32_e32 v15, v15, v15
	v_fmac_f32_e32 v9, 0x43800000, v15
	v_fma_f32 v15, v226, s22, -v14
	v_mul_f32_e32 v15, v15, v15
	v_fmac_f32_e32 v9, 0x43800000, v15
	v_fma_f32 v15, v228, s22, -v14
	v_mul_f32_e32 v15, v15, v15
	v_fmac_f32_e32 v9, 0x43800000, v15
	v_fmamk_f32 v9, v9, 0x3a000000, v250
	v_mul_f32_e32 v15, 0x4f800000, v9
	v_cmp_gt_f32_e32 vcc, s15, v9
	s_nop 1
	v_cndmask_b32_e32 v2, v9, v15, vcc
	v_sqrt_f32_e32 v3, v2
	s_nop 1
	v_add_u32_e32 v4, -1, v3
	v_fma_f32 v5, -v4, v3, v2
	v_cmp_ge_f32_e64 s[24:25], 0, v5
	v_add_u32_e32 v5, 1, v3
	v_fma_f32 v6, -v5, v3, v2
	s_nop 0
	v_cndmask_b32_e64 v4, v3, v4, s[24:25]
	v_cmp_lt_f32_e64 s[24:25], 0, v6
	s_nop 1
	v_cndmask_b32_e64 v4, v4, v5, s[24:25]
	v_mul_f32_e32 v5, 0x37800000, v4
	v_cndmask_b32_e32 v4, v4, v5, vcc
	v_cmp_class_f32_e32 vcc, v2, v251
	s_nop 1
	v_cndmask_b32_e32 v2, v4, v2, vcc
	v_div_scale_f32 v3, s[24:25], v2, v2, 1.0
	v_rcp_f32_e32 v4, v3
	s_nop 1
	v_fma_f32 v5, -v3, v4, 1.0
	v_fmac_f32_e32 v4, v5, v4
	v_div_scale_f32 v5, vcc, 1.0, v2, 1.0
	v_mul_f32_e32 v6, v5, v4
	v_fma_f32 v7, -v3, v6, v5
	v_fmac_f32_e32 v6, v7, v4
	v_fma_f32 v5, -v3, v6, v5
	s_nop 1
	v_div_fmas_f32 v3, v5, v4, v6
	v_div_fixup_f32 v9, v3, v2, 1.0
	s_cmp_lg_u32 s23, 0
	s_cbranch_scc1 .Lln1_nopub0
	s_mov_b64 s[26:27], exec
	s_mov_b64 exec, 0xffff
	v_add_u32_e32 v253, 0x0, v249
	global_store_dwordx2 v253, v[8:9], s[10:11]
	s_mov_b64 exec, s[26:27]
; __device__ __forceinline__ unsigned cvt_pk_bf16(float lo, float hi) { unsigned r; asm volatile("v_cvt_pk_bf16_f32 %0, %1, %2" : "=v"(r) : "v"(lo), "v"(hi)); return r; }
; __global__ void __launch_bounds__(512, 2) fwd_kernel(Args a) {
;     ...
;             const float rstd_a = 1.0f / sqrtf(wave_sum(qa) * (1.0f / DMODEL) + LN_EPS), rstd_b = 1.0f / sqrtf(wave_sum(qb_) * (1.0f / DMODEL) + LN_EPS);
;             u32x2* o8 = (u32x2*)(ubuf + (size_t)m * DMODEL) + lane;
;             f32x4 ggv[8], bbv[8], shv[8], scv[8];
; #pragma unroll
;             for (int j = 0; j < 8; ++j) { const int col = 4 * lane + 256 * j; ggv[j] = *(const f32x4*)(lng_p + col); bbv[j] = *(const f32x4*)(lnb_p + col);
;                 shv[j] = *(const f32x4*)(md + 3 * DMODEL + col); scv[j] = *(const f32x4*)(md + 4 * DMODEL + col); }
; #pragma unroll
;             for (int j = 0; j < 8; ++j) { const f32x4 gg = ggv[j], bb = bbv[j];
;                 const f32x4 ya = va[j] * rstd_a * gg + bb, yb = vb[j] * rstd_b * gg + bb; __builtin_nontemporal_store(ya, xr + 64 * j); __builtin_nontemporal_store(yb, xr + 512 + 64 * j);
;                 const f32x4 sh = shv[j], sc = scv[j] + 1.0f;
;                 const f32x4 ua = ya * sc + sh, ub = yb * sc + sh; u32x2 wa, wb;
;                 wa.x = pg8::cvt_pk_bf16(ua[0], ua[1]); wa.y = pg8::cvt_pk_bf16(ua[2], ua[3]); wb.x = pg8::cvt_pk_bf16(ub[0], ub[1]); wb.y = pg8::cvt_pk_bf16(ub[2], ub[3]);
;                 o8[64 * j] = wa; o8[512 + 64 * j] = wb; } }
.Lln1_nopub0:
	v_pk_fma_f32 v[126:127], v[8:9], v[10:11], v[126:127] op_sel:[0,1,0] op_sel_hi:[0,1,1]
	v_pk_mul_f32 v[126:127], v[126:127], v[8:9] op_sel:[0,1] op_sel_hi:[1,1]
	v_pk_fma_f32 v[126:127], v[130:131], v[126:127], v[146:147]
	v_pk_fma_f32 v[126:127], v[126:127], v[178:179], v[162:163]
	v_pk_fma_f32 v[128:129], v[8:9], v[10:11], v[128:129] op_sel:[0,1,0] op_sel_hi:[0,1,1]
	v_pk_mul_f32 v[128:129], v[128:129], v[8:9] op_sel:[0,1] op_sel_hi:[1,1]
	v_pk_fma_f32 v[128:129], v[132:133], v[128:129], v[148:149]
	v_pk_fma_f32 v[128:129], v[128:129], v[180:181], v[164:165]
	v_cvt_pk_bf16_f32 v126, v126, v127
	v_cvt_pk_bf16_f32 v127, v128, v129
	global_store_dwordx2 v[246:247], v[126:127], off
	v_pk_fma_f32 v[122:123], v[8:9], v[10:11], v[122:123] op_sel:[0,1,0] op_sel_hi:[0,1,1]
	v_pk_mul_f32 v[122:123], v[122:123], v[8:9] op_sel:[0,1] op_sel_hi:[1,1]
	v_pk_fma_f32 v[122:123], v[134:135], v[122:123], v[150:151]
	v_pk_fma_f32 v[122:123], v[122:123], v[182:183], v[166:167]
	v_pk_fma_f32 v[124:125], v[8:9], v[10:11], v[124:125] op_sel:[0,1,0] op_sel_hi:[0,1,1]
	v_pk_mul_f32 v[124:125], v[124:125], v[8:9] op_sel:[0,1] op_sel_hi:[1,1]
	v_pk_fma_f32 v[124:125], v[136:137], v[124:125], v[152:153]
	v_pk_fma_f32 v[124:125], v[124:125], v[184:185], v[168:169]
	v_cvt_pk_bf16_f32 v122, v122, v123
	v_cvt_pk_bf16_f32 v123, v124, v125
	global_store_dwordx2 v[246:247], v[122:123], off offset:32
	v_pk_fma_f32 v[62:63], v[8:9], v[10:11], v[62:63] op_sel:[0,1,0] op_sel_hi:[0,1,1]
	v_pk_mul_f32 v[62:63], v[62:63], v[8:9] op_sel:[0,1] op_sel_hi:[1,1]
	v_pk_fma_f32 v[62:63], v[138:139], v[62:63], v[154:155]
	v_pk_fma_f32 v[62:63], v[62:63], v[186:187], v[170:171]
	v_pk_fma_f32 v[64:65], v[8:9], v[10:11], v[64:65] op_sel:[0,1,0] op_sel_hi:[0,1,1]
	v_pk_mul_f32 v[64:65], v[64:65], v[8:9] op_sel:[0,1] op_sel_hi:[1,1]
	v_pk_fma_f32 v[64:65], v[140:141], v[64:65], v[156:157]
	v_pk_fma_f32 v[64:65], v[64:65], v[188:189], v[172:173]
	v_cvt_pk_bf16_f32 v62, v62, v63
	v_cvt_pk_bf16_f32 v63, v64, v65
	global_store_dwordx2 v[246:247], v[62:63], off offset:256
	v_pk_fma_f32 v[58:59], v[8:9], v[10:11], v[58:59] op_sel:[0,1,0] op_sel_hi:[0,1,1]
	v_pk_mul_f32 v[58:59], v[58:59], v[8:9] op_sel:[0,1] op_sel_hi:[1,1]
	v_pk_fma_f32 v[58:59], v[142:143], v[58:59], v[158:159]
	v_pk_fma_f32 v[58:59], v[58:59], v[190:191], v[174:175]
	v_pk_fma_f32 v[60:61], v[8:9], v[10:11], v[60:61] op_sel:[0,1,0] op_sel_hi:[0,1,1]
	v_pk_mul_f32 v[60:61], v[60:61], v[8:9] op_sel:[0,1] op_sel_hi:[1,1]
	v_pk_fma_f32 v[60:61], v[144:145], v[60:61], v[160:161]
	v_pk_fma_f32 v[60:61], v[60:61], v[192:193], v[176:177]
	v_cvt_pk_bf16_f32 v58, v58, v59
	v_cvt_pk_bf16_f32 v59, v60, v61
	global_store_dwordx2 v[246:247], v[58:59], off offset:288
	v_add_u32_e32 v252, 0x800, v248
	global_load_dwordx4 v[214:217], v252, s[8:9]
	global_load_dwordx4 v[218:221], v252, s[8:9] offset:16
	global_load_dwordx4 v[222:225], v252, s[8:9] offset:32
	global_load_dwordx4 v[226:229], v252, s[8:9] offset:48
	s_waitcnt vmcnt(8)
	v_add_f32_e32 v8, v230, v232
	v_add_f32_e32 v8, v8, v234
	v_add_f32_e32 v8, v8, v236
	v_add_f32_e32 v8, v8, v238
	v_add_f32_e32 v8, v8, v240
	v_add_f32_e32 v8, v8, v242
	v_add_f32_e32 v8, v8, v244
	v_mul_f32_e32 v14, 0x3a000000, v8
	v_add_f32_e32 v9, v231, v233
	v_add_f32_e32 v9, v9, v235
	v_add_f32_e32 v9, v9, v237
	v_add_f32_e32 v9, v9, v239
	v_add_f32_e32 v9, v9, v241
	v_add_f32_e32 v9, v9, v243
	v_add_f32_e32 v9, v9, v245
	v_fma_f32 v15, v230, s22, -v14
	v_mul_f32_e32 v15, v15, v15
	v_fmac_f32_e32 v9, 0x43800000, v15
	v_fma_f32 v15, v232, s22, -v14
	v_mul_f32_e32 v15, v15, v15
	v_fmac_f32_e32 v9, 0x43800000, v15
	v_fma_f32 v15, v234, s22, -v14
	v_mul_f32_e32 v15, v15, v15
	v_fmac_f32_e32 v9, 0x43800000, v15
	v_fma_f32 v15, v236, s22, -v14
	v_mul_f32_e32 v15, v15, v15
	v_fmac_f32_e32 v9, 0x43800000, v15
	v_fma_f32 v15, v238, s22, -v14
	v_mul_f32_e32 v15, v15, v15
	v_fmac_f32_e32 v9, 0x43800000, v15
	v_fma_f32 v15, v240, s22, -v14
	v_mul_f32_e32 v15, v15, v15
	v_fmac_f32_e32 v9, 0x43800000, v15
	v_fma_f32 v15, v242, s22, -v14
	v_mul_f32_e32 v15, v15, v15
	v_fmac_f32_e32 v9, 0x43800000, v15
	v_fma_f32 v15, v244, s22, -v14
	v_mul_f32_e32 v15, v15, v15
	v_fmac_f32_e32 v9, 0x43800000, v15
	v_fmamk_f32 v9, v9, 0x3a000000, v250
	v_mul_f32_e32 v15, 0x4f800000, v9
	v_cmp_gt_f32_e32 vcc, s15, v9
	s_nop 1
	v_cndmask_b32_e32 v2, v9, v15, vcc
	v_sqrt_f32_e32 v3, v2
	s_nop 1
	v_add_u32_e32 v4, -1, v3
	v_fma_f32 v5, -v4, v3, v2
	v_cmp_ge_f32_e64 s[24:25], 0, v5
	v_add_u32_e32 v5, 1, v3
	v_fma_f32 v6, -v5, v3, v2
	s_nop 0
	v_cndmask_b32_e64 v4, v3, v4, s[24:25]
	v_cmp_lt_f32_e64 s[24:25], 0, v6
	s_nop 1
	v_cndmask_b32_e64 v4, v4, v5, s[24:25]
	v_mul_f32_e32 v5, 0x37800000, v4
	v_cndmask_b32_e32 v4, v4, v5, vcc
	v_cmp_class_f32_e32 vcc, v2, v251
	s_nop 1
	v_cndmask_b32_e32 v2, v4, v2, vcc
	v_div_scale_f32 v3, s[24:25], v2, v2, 1.0
	v_rcp_f32_e32 v4, v3
	s_nop 1
	v_fma_f32 v5, -v3, v4, 1.0
	v_fmac_f32_e32 v4, v5, v4
	v_div_scale_f32 v5, vcc, 1.0, v2, 1.0
	v_mul_f32_e32 v6, v5, v4
	v_fma_f32 v7, -v3, v6, v5
	v_fmac_f32_e32 v6, v7, v4
	v_fma_f32 v5, -v3, v6, v5
	s_nop 1
	v_div_fmas_f32 v3, v5, v4, v6
	v_div_fixup_f32 v9, v3, v2, 1.0
	s_cmp_lg_u32 s23, 0
	s_cbranch_scc1 .Lln1_nopub1
	s_mov_b64 s[26:27], exec
	s_mov_b64 exec, 0xffff
	v_add_u32_e32 v253, 0x80, v249
	global_store_dwordx2 v253, v[8:9], s[10:11]
	s_mov_b64 exec, s[26:27]
; __device__ __forceinline__ unsigned cvt_pk_bf16(float lo, float hi) { unsigned r; asm volatile("v_cvt_pk_bf16_f32 %0, %1, %2" : "=v"(r) : "v"(lo), "v"(hi)); return r; }
; __global__ void __launch_bounds__(512, 2) fwd_kernel(Args a) {
;     ...
;             const float rstd_a = 1.0f / sqrtf(wave_sum(qa) * (1.0f / DMODEL) + LN_EPS), rstd_b = 1.0f / sqrtf(wave_sum(qb_) * (1.0f / DMODEL) + LN_EPS);
;             u32x2* o8 = (u32x2*)(ubuf + (size_t)m * DMODEL) + lane;
;             f32x4 ggv[8], bbv[8], shv[8], scv[8];
; #pragma unroll
;             for (int j = 0; j < 8; ++j) { const int col = 4 * lane + 256 * j; ggv[j] = *(const f32x4*)(lng_p + col); bbv[j] = *(const f32x4*)(lnb_p + col);
;                 shv[j] = *(const f32x4*)(md + 3 * DMODEL + col); scv[j] = *(const f32x4*)(md + 4 * DMODEL + col); }
; #pragma unroll
;             for (int j = 0; j < 8; ++j) { const f32x4 gg = ggv[j], bb = bbv[j];
;                 const f32x4 ya = va[j] * rstd_a * gg + bb, yb = vb[j] * rstd_b * gg + bb; __builtin_nontemporal_store(ya, xr + 64 * j); __builtin_nontemporal_store(yb, xr + 512 + 64 * j);
;                 const f32x4 sh = shv[j], sc = scv[j] + 1.0f;
;                 const f32x4 ua = ya * sc + sh, ub = yb * sc + sh; u32x2 wa, wb;
;                 wa.x = pg8::cvt_pk_bf16(ua[0], ua[1]); wa.y = pg8::cvt_pk_bf16(ua[2], ua[3]); wb.x = pg8::cvt_pk_bf16(ub[0], ub[1]); wb.y = pg8::cvt_pk_bf16(ub[2], ub[3]);
;                 o8[64 * j] = wa; o8[512 + 64 * j] = wb; } }
.Lln1_nopub1:
	s_mov_b64 s[28:29], 0x10000
	v_lshl_add_u64 v[12:13], v[246:247], 0, s[28:29]
	v_pk_fma_f32 v[118:119], v[8:9], v[10:11], v[118:119] op_sel:[0,1,0] op_sel_hi:[0,1,1]
	v_pk_mul_f32 v[118:119], v[118:119], v[8:9] op_sel:[0,1] op_sel_hi:[1,1]
	v_pk_fma_f32 v[118:119], v[130:131], v[118:119], v[146:147]
	v_pk_fma_f32 v[118:119], v[118:119], v[178:179], v[162:163]
	v_pk_fma_f32 v[120:121], v[8:9], v[10:11], v[120:121] op_sel:[0,1,0] op_sel_hi:[0,1,1]
	v_pk_mul_f32 v[120:121], v[120:121], v[8:9] op_sel:[0,1] op_sel_hi:[1,1]
	v_pk_fma_f32 v[120:121], v[132:133], v[120:121], v[148:149]
	v_pk_fma_f32 v[120:121], v[120:121], v[180:181], v[164:165]
	v_cvt_pk_bf16_f32 v118, v118, v119
	v_cvt_pk_bf16_f32 v119, v120, v121
	global_store_dwordx2 v[12:13], v[118:119], off
	v_pk_fma_f32 v[114:115], v[8:9], v[10:11], v[114:115] op_sel:[0,1,0] op_sel_hi:[0,1,1]
	v_pk_mul_f32 v[114:115], v[114:115], v[8:9] op_sel:[0,1] op_sel_hi:[1,1]
	v_pk_fma_f32 v[114:115], v[134:135], v[114:115], v[150:151]
	v_pk_fma_f32 v[114:115], v[114:115], v[182:183], v[166:167]
	v_pk_fma_f32 v[116:117], v[8:9], v[10:11], v[116:117] op_sel:[0,1,0] op_sel_hi:[0,1,1]
	v_pk_mul_f32 v[116:117], v[116:117], v[8:9] op_sel:[0,1] op_sel_hi:[1,1]
	v_pk_fma_f32 v[116:117], v[136:137], v[116:117], v[152:153]
	v_pk_fma_f32 v[116:117], v[116:117], v[184:185], v[168:169]
	v_cvt_pk_bf16_f32 v114, v114, v115
	v_cvt_pk_bf16_f32 v115, v116, v117
	global_store_dwordx2 v[12:13], v[114:115], off offset:32
	v_pk_fma_f32 v[54:55], v[8:9], v[10:11], v[54:55] op_sel:[0,1,0] op_sel_hi:[0,1,1]
	v_pk_mul_f32 v[54:55], v[54:55], v[8:9] op_sel:[0,1] op_sel_hi:[1,1]
	v_pk_fma_f32 v[54:55], v[138:139], v[54:55], v[154:155]
	v_pk_fma_f32 v[54:55], v[54:55], v[186:187], v[170:171]
	v_pk_fma_f32 v[56:57], v[8:9], v[10:11], v[56:57] op_sel:[0,1,0] op_sel_hi:[0,1,1]
	v_pk_mul_f32 v[56:57], v[56:57], v[8:9] op_sel:[0,1] op_sel_hi:[1,1]
	v_pk_fma_f32 v[56:57], v[140:141], v[56:57], v[156:157]
	v_pk_fma_f32 v[56:57], v[56:57], v[188:189], v[172:173]
	v_cvt_pk_bf16_f32 v54, v54, v55
	v_cvt_pk_bf16_f32 v55, v56, v57
	global_store_dwordx2 v[12:13], v[54:55], off offset:256
	v_pk_fma_f32 v[50:51], v[8:9], v[10:11], v[50:51] op_sel:[0,1,0] op_sel_hi:[0,1,1]
	v_pk_mul_f32 v[50:51], v[50:51], v[8:9] op_sel:[0,1] op_sel_hi:[1,1]
	v_pk_fma_f32 v[50:51], v[142:143], v[50:51], v[158:159]
	v_pk_fma_f32 v[50:51], v[50:51], v[190:191], v[174:175]
	v_pk_fma_f32 v[52:53], v[8:9], v[10:11], v[52:53] op_sel:[0,1,0] op_sel_hi:[0,1,1]
	v_pk_mul_f32 v[52:53], v[52:53], v[8:9] op_sel:[0,1] op_sel_hi:[1,1]
	v_pk_fma_f32 v[52:53], v[144:145], v[52:53], v[160:161]
	v_pk_fma_f32 v[52:53], v[52:53], v[192:193], v[176:177]
	v_cvt_pk_bf16_f32 v50, v50, v51
	v_cvt_pk_bf16_f32 v51, v52, v53
	global_store_dwordx2 v[12:13], v[50:51], off offset:288
	v_add_u32_e32 v252, 0xc00, v248
	global_load_dwordx4 v[230:233], v252, s[8:9]
	global_load_dwordx4 v[234:237], v252, s[8:9] offset:16
	global_load_dwordx4 v[238:241], v252, s[8:9] offset:32
	global_load_dwordx4 v[242:245], v252, s[8:9] offset:48
	s_waitcnt vmcnt(8)
	v_add_f32_e32 v8, v214, v216
	v_add_f32_e32 v8, v8, v218
	v_add_f32_e32 v8, v8, v220
	v_add_f32_e32 v8, v8, v222
	v_add_f32_e32 v8, v8, v224
	v_add_f32_e32 v8, v8, v226
	v_add_f32_e32 v8, v8, v228
	v_mul_f32_e32 v14, 0x3a000000, v8
	v_add_f32_e32 v9, v215, v217
	v_add_f32_e32 v9, v9, v219
	v_add_f32_e32 v9, v9, v221
	v_add_f32_e32 v9, v9, v223
	v_add_f32_e32 v9, v9, v225
	v_add_f32_e32 v9, v9, v227
	v_add_f32_e32 v9, v9, v229
	v_fma_f32 v15, v214, s22, -v14
	v_mul_f32_e32 v15, v15, v15
	v_fmac_f32_e32 v9, 0x43800000, v15
	v_fma_f32 v15, v216, s22, -v14
	v_mul_f32_e32 v15, v15, v15
	v_fmac_f32_e32 v9, 0x43800000, v15
	v_fma_f32 v15, v218, s22, -v14
	v_mul_f32_e32 v15, v15, v15
	v_fmac_f32_e32 v9, 0x43800000, v15
	v_fma_f32 v15, v220, s22, -v14
	v_mul_f32_e32 v15, v15, v15
	v_fmac_f32_e32 v9, 0x43800000, v15
	v_fma_f32 v15, v222, s22, -v14
	v_mul_f32_e32 v15, v15, v15
	v_fmac_f32_e32 v9, 0x43800000, v15
	v_fma_f32 v15, v224, s22, -v14
	v_mul_f32_e32 v15, v15, v15
	v_fmac_f32_e32 v9, 0x43800000, v15
	v_fma_f32 v15, v226, s22, -v14
	v_mul_f32_e32 v15, v15, v15
	v_fmac_f32_e32 v9, 0x43800000, v15
	v_fma_f32 v15, v228, s22, -v14
	v_mul_f32_e32 v15, v15, v15
	v_fmac_f32_e32 v9, 0x43800000, v15
	v_fmamk_f32 v9, v9, 0x3a000000, v250
	v_mul_f32_e32 v15, 0x4f800000, v9
	v_cmp_gt_f32_e32 vcc, s15, v9
	s_nop 1
	v_cndmask_b32_e32 v2, v9, v15, vcc
	v_sqrt_f32_e32 v3, v2
	s_nop 1
	v_add_u32_e32 v4, -1, v3
	v_fma_f32 v5, -v4, v3, v2
	v_cmp_ge_f32_e64 s[24:25], 0, v5
	v_add_u32_e32 v5, 1, v3
	v_fma_f32 v6, -v5, v3, v2
	s_nop 0
	v_cndmask_b32_e64 v4, v3, v4, s[24:25]
	v_cmp_lt_f32_e64 s[24:25], 0, v6
	s_nop 1
	v_cndmask_b32_e64 v4, v4, v5, s[24:25]
	v_mul_f32_e32 v5, 0x37800000, v4
	v_cndmask_b32_e32 v4, v4, v5, vcc
	v_cmp_class_f32_e32 vcc, v2, v251
	s_nop 1
	v_cndmask_b32_e32 v2, v4, v2, vcc
	v_div_scale_f32 v3, s[24:25], v2, v2, 1.0
	v_rcp_f32_e32 v4, v3
	s_nop 1
	v_fma_f32 v5, -v3, v4, 1.0
	v_fmac_f32_e32 v4, v5, v4
	v_div_scale_f32 v5, vcc, 1.0, v2, 1.0
	v_mul_f32_e32 v6, v5, v4
	v_fma_f32 v7, -v3, v6, v5
	v_fmac_f32_e32 v6, v7, v4
	v_fma_f32 v5, -v3, v6, v5
	s_nop 1
	v_div_fmas_f32 v3, v5, v4, v6
	v_div_fixup_f32 v9, v3, v2, 1.0
	s_cmp_lg_u32 s23, 0
	s_cbranch_scc1 .Lln1_nopub2
	s_mov_b64 s[26:27], exec
	s_mov_b64 exec, 0xffff
	v_add_u32_e32 v253, 0x100, v249
	global_store_dwordx2 v253, v[8:9], s[10:11]
	s_mov_b64 exec, s[26:27]
; __device__ __forceinline__ unsigned cvt_pk_bf16(float lo, float hi) { unsigned r; asm volatile("v_cvt_pk_bf16_f32 %0, %1, %2" : "=v"(r) : "v"(lo), "v"(hi)); return r; }
; __global__ void __launch_bounds__(512, 2) fwd_kernel(Args a) {
;     ...
;             const float rstd_a = 1.0f / sqrtf(wave_sum(qa) * (1.0f / DMODEL) + LN_EPS), rstd_b = 1.0f / sqrtf(wave_sum(qb_) * (1.0f / DMODEL) + LN_EPS);
;             u32x2* o8 = (u32x2*)(ubuf + (size_t)m * DMODEL) + lane;
;             f32x4 ggv[8], bbv[8], shv[8], scv[8];
; #pragma unroll
;             for (int j = 0; j < 8; ++j) { const int col = 4 * lane + 256 * j; ggv[j] = *(const f32x4*)(lng_p + col); bbv[j] = *(const f32x4*)(lnb_p + col);
;                 shv[j] = *(const f32x4*)(md + 3 * DMODEL + col); scv[j] = *(const f32x4*)(md + 4 * DMODEL + col); }
; #pragma unroll
;             for (int j = 0; j < 8; ++j) { const f32x4 gg = ggv[j], bb = bbv[j];
;                 const f32x4 ya = va[j] * rstd_a * gg + bb, yb = vb[j] * rstd_b * gg + bb; __builtin_nontemporal_store(ya, xr + 64 * j); __builtin_nontemporal_store(yb, xr + 512 + 64 * j);
;                 const f32x4 sh = shv[j], sc = scv[j] + 1.0f;
;                 const f32x4 ua = ya * sc + sh, ub = yb * sc + sh; u32x2 wa, wb;
;                 wa.x = pg8::cvt_pk_bf16(ua[0], ua[1]); wa.y = pg8::cvt_pk_bf16(ua[2], ua[3]); wb.x = pg8::cvt_pk_bf16(ub[0], ub[1]); wb.y = pg8::cvt_pk_bf16(ub[2], ub[3]);
;                 o8[64 * j] = wa; o8[512 + 64 * j] = wb; } }
.Lln1_nopub2:
	s_mov_b64 s[28:29], 0x20000
	v_lshl_add_u64 v[12:13], v[246:247], 0, s[28:29]
	v_pk_fma_f32 v[110:111], v[8:9], v[10:11], v[110:111] op_sel:[0,1,0] op_sel_hi:[0,1,1]
	v_pk_mul_f32 v[110:111], v[110:111], v[8:9] op_sel:[0,1] op_sel_hi:[1,1]
	v_pk_fma_f32 v[110:111], v[130:131], v[110:111], v[146:147]
	v_pk_fma_f32 v[110:111], v[110:111], v[178:179], v[162:163]
	v_pk_fma_f32 v[112:113], v[8:9], v[10:11], v[112:113] op_sel:[0,1,0] op_sel_hi:[0,1,1]
	v_pk_mul_f32 v[112:113], v[112:113], v[8:9] op_sel:[0,1] op_sel_hi:[1,1]
	v_pk_fma_f32 v[112:113], v[132:133], v[112:113], v[148:149]
	v_pk_fma_f32 v[112:113], v[112:113], v[180:181], v[164:165]
	v_cvt_pk_bf16_f32 v110, v110, v111
	v_cvt_pk_bf16_f32 v111, v112, v113
	global_store_dwordx2 v[12:13], v[110:111], off
	v_pk_fma_f32 v[106:107], v[8:9], v[10:11], v[106:107] op_sel:[0,1,0] op_sel_hi:[0,1,1]
	v_pk_mul_f32 v[106:107], v[106:107], v[8:9] op_sel:[0,1] op_sel_hi:[1,1]
	v_pk_fma_f32 v[106:107], v[134:135], v[106:107], v[150:151]
	v_pk_fma_f32 v[106:107], v[106:107], v[182:183], v[166:167]
	v_pk_fma_f32 v[108:109], v[8:9], v[10:11], v[108:109] op_sel:[0,1,0] op_sel_hi:[0,1,1]
	v_pk_mul_f32 v[108:109], v[108:109], v[8:9] op_sel:[0,1] op_sel_hi:[1,1]
	v_pk_fma_f32 v[108:109], v[136:137], v[108:109], v[152:153]
	v_pk_fma_f32 v[108:109], v[108:109], v[184:185], v[168:169]
	v_cvt_pk_bf16_f32 v106, v106, v107
	v_cvt_pk_bf16_f32 v107, v108, v109
	global_store_dwordx2 v[12:13], v[106:107], off offset:32
	v_pk_fma_f32 v[46:47], v[8:9], v[10:11], v[46:47] op_sel:[0,1,0] op_sel_hi:[0,1,1]
	v_pk_mul_f32 v[46:47], v[46:47], v[8:9] op_sel:[0,1] op_sel_hi:[1,1]
	v_pk_fma_f32 v[46:47], v[138:139], v[46:47], v[154:155]
	v_pk_fma_f32 v[46:47], v[46:47], v[186:187], v[170:171]
	v_pk_fma_f32 v[48:49], v[8:9], v[10:11], v[48:49] op_sel:[0,1,0] op_sel_hi:[0,1,1]
	v_pk_mul_f32 v[48:49], v[48:49], v[8:9] op_sel:[0,1] op_sel_hi:[1,1]
	v_pk_fma_f32 v[48:49], v[140:141], v[48:49], v[156:157]
	v_pk_fma_f32 v[48:49], v[48:49], v[188:189], v[172:173]
	v_cvt_pk_bf16_f32 v46, v46, v47
	v_cvt_pk_bf16_f32 v47, v48, v49
	global_store_dwordx2 v[12:13], v[46:47], off offset:256
	v_pk_fma_f32 v[42:43], v[8:9], v[10:11], v[42:43] op_sel:[0,1,0] op_sel_hi:[0,1,1]
	v_pk_mul_f32 v[42:43], v[42:43], v[8:9] op_sel:[0,1] op_sel_hi:[1,1]
	v_pk_fma_f32 v[42:43], v[142:143], v[42:43], v[158:159]
	v_pk_fma_f32 v[42:43], v[42:43], v[190:191], v[174:175]
	v_pk_fma_f32 v[44:45], v[8:9], v[10:11], v[44:45] op_sel:[0,1,0] op_sel_hi:[0,1,1]
	v_pk_mul_f32 v[44:45], v[44:45], v[8:9] op_sel:[0,1] op_sel_hi:[1,1]
	v_pk_fma_f32 v[44:45], v[144:145], v[44:45], v[160:161]
	v_pk_fma_f32 v[44:45], v[44:45], v[192:193], v[176:177]
	v_cvt_pk_bf16_f32 v42, v42, v43
	v_cvt_pk_bf16_f32 v43, v44, v45
	global_store_dwordx2 v[12:13], v[42:43], off offset:288
	v_add_u32_e32 v252, 0x2000, v248
	global_load_dwordx4 v[214:217], v252, s[8:9]
	global_load_dwordx4 v[218:221], v252, s[8:9] offset:16
	global_load_dwordx4 v[222:225], v252, s[8:9] offset:32
	global_load_dwordx4 v[226:229], v252, s[8:9] offset:48
	s_waitcnt vmcnt(8)
	v_add_f32_e32 v8, v230, v232
	v_add_f32_e32 v8, v8, v234
	v_add_f32_e32 v8, v8, v236
	v_add_f32_e32 v8, v8, v238
	v_add_f32_e32 v8, v8, v240
	v_add_f32_e32 v8, v8, v242
	v_add_f32_e32 v8, v8, v244
	v_mul_f32_e32 v14, 0x3a000000, v8
	v_add_f32_e32 v9, v231, v233
	v_add_f32_e32 v9, v9, v235
	v_add_f32_e32 v9, v9, v237
	v_add_f32_e32 v9, v9, v239
	v_add_f32_e32 v9, v9, v241
	v_add_f32_e32 v9, v9, v243
	v_add_f32_e32 v9, v9, v245
	v_fma_f32 v15, v230, s22, -v14
	v_mul_f32_e32 v15, v15, v15
	v_fmac_f32_e32 v9, 0x43800000, v15
	v_fma_f32 v15, v232, s22, -v14
	v_mul_f32_e32 v15, v15, v15
	v_fmac_f32_e32 v9, 0x43800000, v15
	v_fma_f32 v15, v234, s22, -v14
	v_mul_f32_e32 v15, v15, v15
	v_fmac_f32_e32 v9, 0x43800000, v15
	v_fma_f32 v15, v236, s22, -v14
	v_mul_f32_e32 v15, v15, v15
	v_fmac_f32_e32 v9, 0x43800000, v15
	v_fma_f32 v15, v238, s22, -v14
	v_mul_f32_e32 v15, v15, v15
	v_fmac_f32_e32 v9, 0x43800000, v15
	v_fma_f32 v15, v240, s22, -v14
	v_mul_f32_e32 v15, v15, v15
	v_fmac_f32_e32 v9, 0x43800000, v15
	v_fma_f32 v15, v242, s22, -v14
	v_mul_f32_e32 v15, v15, v15
	v_fmac_f32_e32 v9, 0x43800000, v15
	v_fma_f32 v15, v244, s22, -v14
	v_mul_f32_e32 v15, v15, v15
	v_fmac_f32_e32 v9, 0x43800000, v15
	v_fmamk_f32 v9, v9, 0x3a000000, v250
	v_mul_f32_e32 v15, 0x4f800000, v9
	v_cmp_gt_f32_e32 vcc, s15, v9
	s_nop 1
	v_cndmask_b32_e32 v2, v9, v15, vcc
	v_sqrt_f32_e32 v3, v2
	s_nop 1
	v_add_u32_e32 v4, -1, v3
	v_fma_f32 v5, -v4, v3, v2
	v_cmp_ge_f32_e64 s[24:25], 0, v5
	v_add_u32_e32 v5, 1, v3
	v_fma_f32 v6, -v5, v3, v2
	s_nop 0
	v_cndmask_b32_e64 v4, v3, v4, s[24:25]
	v_cmp_lt_f32_e64 s[24:25], 0, v6
	s_nop 1
	v_cndmask_b32_e64 v4, v4, v5, s[24:25]
	v_mul_f32_e32 v5, 0x37800000, v4
	v_cndmask_b32_e32 v4, v4, v5, vcc
	v_cmp_class_f32_e32 vcc, v2, v251
	s_nop 1
	v_cndmask_b32_e32 v2, v4, v2, vcc
	v_div_scale_f32 v3, s[24:25], v2, v2, 1.0
	v_rcp_f32_e32 v4, v3
	s_nop 1
	v_fma_f32 v5, -v3, v4, 1.0
	v_fmac_f32_e32 v4, v5, v4
	v_div_scale_f32 v5, vcc, 1.0, v2, 1.0
	v_mul_f32_e32 v6, v5, v4
	v_fma_f32 v7, -v3, v6, v5
	v_fmac_f32_e32 v6, v7, v4
	v_fma_f32 v5, -v3, v6, v5
	s_nop 1
	v_div_fmas_f32 v3, v5, v4, v6
	v_div_fixup_f32 v9, v3, v2, 1.0
	s_cmp_lg_u32 s23, 0
	s_cbranch_scc1 .Lln1_nopub3
	s_mov_b64 s[26:27], exec
	s_mov_b64 exec, 0xffff
	v_add_u32_e32 v253, 0x180, v249
	global_store_dwordx2 v253, v[8:9], s[10:11]
	s_mov_b64 exec, s[26:27]
; __device__ __forceinline__ unsigned cvt_pk_bf16(float lo, float hi) { unsigned r; asm volatile("v_cvt_pk_bf16_f32 %0, %1, %2" : "=v"(r) : "v"(lo), "v"(hi)); return r; }
; __global__ void __launch_bounds__(512, 2) fwd_kernel(Args a) {
;     ...
;             const float rstd_a = 1.0f / sqrtf(wave_sum(qa) * (1.0f / DMODEL) + LN_EPS), rstd_b = 1.0f / sqrtf(wave_sum(qb_) * (1.0f / DMODEL) + LN_EPS);
;             u32x2* o8 = (u32x2*)(ubuf + (size_t)m * DMODEL) + lane;
;             f32x4 ggv[8], bbv[8], shv[8], scv[8];
; #pragma unroll
;             for (int j = 0; j < 8; ++j) { const int col = 4 * lane + 256 * j; ggv[j] = *(const f32x4*)(lng_p + col); bbv[j] = *(const f32x4*)(lnb_p + col);
;                 shv[j] = *(const f32x4*)(md + 3 * DMODEL + col); scv[j] = *(const f32x4*)(md + 4 * DMODEL + col); }
; #pragma unroll
;             for (int j = 0; j < 8; ++j) { const f32x4 gg = ggv[j], bb = bbv[j];
;                 const f32x4 ya = va[j] * rstd_a * gg + bb, yb = vb[j] * rstd_b * gg + bb; __builtin_nontemporal_store(ya, xr + 64 * j); __builtin_nontemporal_store(yb, xr + 512 + 64 * j);
;                 const f32x4 sh = shv[j], sc = scv[j] + 1.0f;
;                 const f32x4 ua = ya * sc + sh, ub = yb * sc + sh; u32x2 wa, wb;
;                 wa.x = pg8::cvt_pk_bf16(ua[0], ua[1]); wa.y = pg8::cvt_pk_bf16(ua[2], ua[3]); wb.x = pg8::cvt_pk_bf16(ub[0], ub[1]); wb.y = pg8::cvt_pk_bf16(ub[2], ub[3]);
;                 o8[64 * j] = wa; o8[512 + 64 * j] = wb; } }
.Lln1_nopub3:
	s_mov_b64 s[28:29], 0x30000
	v_lshl_add_u64 v[12:13], v[246:247], 0, s[28:29]
	v_pk_fma_f32 v[102:103], v[8:9], v[10:11], v[102:103] op_sel:[0,1,0] op_sel_hi:[0,1,1]
	v_pk_mul_f32 v[102:103], v[102:103], v[8:9] op_sel:[0,1] op_sel_hi:[1,1]
	v_pk_fma_f32 v[102:103], v[130:131], v[102:103], v[146:147]
	v_pk_fma_f32 v[102:103], v[102:103], v[178:179], v[162:163]
	v_pk_fma_f32 v[104:105], v[8:9], v[10:11], v[104:105] op_sel:[0,1,0] op_sel_hi:[0,1,1]
	v_pk_mul_f32 v[104:105], v[104:105], v[8:9] op_sel:[0,1] op_sel_hi:[1,1]
	v_pk_fma_f32 v[104:105], v[132:133], v[104:105], v[148:149]
	v_pk_fma_f32 v[104:105], v[104:105], v[180:181], v[164:165]
	v_cvt_pk_bf16_f32 v102, v102, v103
	v_cvt_pk_bf16_f32 v103, v104, v105
	global_store_dwordx2 v[12:13], v[102:103], off
	v_pk_fma_f32 v[98:99], v[8:9], v[10:11], v[98:99] op_sel:[0,1,0] op_sel_hi:[0,1,1]
	v_pk_mul_f32 v[98:99], v[98:99], v[8:9] op_sel:[0,1] op_sel_hi:[1,1]
	v_pk_fma_f32 v[98:99], v[134:135], v[98:99], v[150:151]
	v_pk_fma_f32 v[98:99], v[98:99], v[182:183], v[166:167]
	v_pk_fma_f32 v[100:101], v[8:9], v[10:11], v[100:101] op_sel:[0,1,0] op_sel_hi:[0,1,1]
	v_pk_mul_f32 v[100:101], v[100:101], v[8:9] op_sel:[0,1] op_sel_hi:[1,1]
	v_pk_fma_f32 v[100:101], v[136:137], v[100:101], v[152:153]
	v_pk_fma_f32 v[100:101], v[100:101], v[184:185], v[168:169]
	v_cvt_pk_bf16_f32 v98, v98, v99
	v_cvt_pk_bf16_f32 v99, v100, v101
	global_store_dwordx2 v[12:13], v[98:99], off offset:32
	v_pk_fma_f32 v[38:39], v[8:9], v[10:11], v[38:39] op_sel:[0,1,0] op_sel_hi:[0,1,1]
	v_pk_mul_f32 v[38:39], v[38:39], v[8:9] op_sel:[0,1] op_sel_hi:[1,1]
	v_pk_fma_f32 v[38:39], v[138:139], v[38:39], v[154:155]
	v_pk_fma_f32 v[38:39], v[38:39], v[186:187], v[170:171]
	v_pk_fma_f32 v[40:41], v[8:9], v[10:11], v[40:41] op_sel:[0,1,0] op_sel_hi:[0,1,1]
	v_pk_mul_f32 v[40:41], v[40:41], v[8:9] op_sel:[0,1] op_sel_hi:[1,1]
	v_pk_fma_f32 v[40:41], v[140:141], v[40:41], v[156:157]
	v_pk_fma_f32 v[40:41], v[40:41], v[188:189], v[172:173]
	v_cvt_pk_bf16_f32 v38, v38, v39
	v_cvt_pk_bf16_f32 v39, v40, v41
	global_store_dwordx2 v[12:13], v[38:39], off offset:256
	v_pk_fma_f32 v[34:35], v[8:9], v[10:11], v[34:35] op_sel:[0,1,0] op_sel_hi:[0,1,1]
	v_pk_mul_f32 v[34:35], v[34:35], v[8:9] op_sel:[0,1] op_sel_hi:[1,1]
	v_pk_fma_f32 v[34:35], v[142:143], v[34:35], v[158:159]
	v_pk_fma_f32 v[34:35], v[34:35], v[190:191], v[174:175]
	v_pk_fma_f32 v[36:37], v[8:9], v[10:11], v[36:37] op_sel:[0,1,0] op_sel_hi:[0,1,1]
	v_pk_mul_f32 v[36:37], v[36:37], v[8:9] op_sel:[0,1] op_sel_hi:[1,1]
	v_pk_fma_f32 v[36:37], v[144:145], v[36:37], v[160:161]
	v_pk_fma_f32 v[36:37], v[36:37], v[192:193], v[176:177]
	v_cvt_pk_bf16_f32 v34, v34, v35
	v_cvt_pk_bf16_f32 v35, v36, v37
	global_store_dwordx2 v[12:13], v[34:35], off offset:288
	v_add_u32_e32 v252, 0x2400, v248
	global_load_dwordx4 v[230:233], v252, s[8:9]
	global_load_dwordx4 v[234:237], v252, s[8:9] offset:16
	global_load_dwordx4 v[238:241], v252, s[8:9] offset:32
	global_load_dwordx4 v[242:245], v252, s[8:9] offset:48
	s_waitcnt vmcnt(8)
	v_add_f32_e32 v8, v214, v216
	v_add_f32_e32 v8, v8, v218
	v_add_f32_e32 v8, v8, v220
	v_add_f32_e32 v8, v8, v222
	v_add_f32_e32 v8, v8, v224
	v_add_f32_e32 v8, v8, v226
	v_add_f32_e32 v8, v8, v228
	v_mul_f32_e32 v14, 0x3a000000, v8
	v_add_f32_e32 v9, v215, v217
	v_add_f32_e32 v9, v9, v219
	v_add_f32_e32 v9, v9, v221
	v_add_f32_e32 v9, v9, v223
	v_add_f32_e32 v9, v9, v225
	v_add_f32_e32 v9, v9, v227
	v_add_f32_e32 v9, v9, v229
	v_fma_f32 v15, v214, s22, -v14
	v_mul_f32_e32 v15, v15, v15
	v_fmac_f32_e32 v9, 0x43800000, v15
	v_fma_f32 v15, v216, s22, -v14
	v_mul_f32_e32 v15, v15, v15
	v_fmac_f32_e32 v9, 0x43800000, v15
	v_fma_f32 v15, v218, s22, -v14
	v_mul_f32_e32 v15, v15, v15
	v_fmac_f32_e32 v9, 0x43800000, v15
	v_fma_f32 v15, v220, s22, -v14
	v_mul_f32_e32 v15, v15, v15
	v_fmac_f32_e32 v9, 0x43800000, v15
	v_fma_f32 v15, v222, s22, -v14
	v_mul_f32_e32 v15, v15, v15
	v_fmac_f32_e32 v9, 0x43800000, v15
	v_fma_f32 v15, v224, s22, -v14
	v_mul_f32_e32 v15, v15, v15
	v_fmac_f32_e32 v9, 0x43800000, v15
	v_fma_f32 v15, v226, s22, -v14
	v_mul_f32_e32 v15, v15, v15
	v_fmac_f32_e32 v9, 0x43800000, v15
	v_fma_f32 v15, v228, s22, -v14
	v_mul_f32_e32 v15, v15, v15
	v_fmac_f32_e32 v9, 0x43800000, v15
	v_fmamk_f32 v9, v9, 0x3a000000, v250
	v_mul_f32_e32 v15, 0x4f800000, v9
	v_cmp_gt_f32_e32 vcc, s15, v9
	s_nop 1
	v_cndmask_b32_e32 v2, v9, v15, vcc
	v_sqrt_f32_e32 v3, v2
	s_nop 1
	v_add_u32_e32 v4, -1, v3
	v_fma_f32 v5, -v4, v3, v2
	v_cmp_ge_f32_e64 s[24:25], 0, v5
	v_add_u32_e32 v5, 1, v3
	v_fma_f32 v6, -v5, v3, v2
	s_nop 0
	v_cndmask_b32_e64 v4, v3, v4, s[24:25]
	v_cmp_lt_f32_e64 s[24:25], 0, v6
	s_nop 1
	v_cndmask_b32_e64 v4, v4, v5, s[24:25]
	v_mul_f32_e32 v5, 0x37800000, v4
	v_cndmask_b32_e32 v4, v4, v5, vcc
	v_cmp_class_f32_e32 vcc, v2, v251
	s_nop 1
	v_cndmask_b32_e32 v2, v4, v2, vcc
	v_div_scale_f32 v3, s[24:25], v2, v2, 1.0
	v_rcp_f32_e32 v4, v3
	s_nop 1
	v_fma_f32 v5, -v3, v4, 1.0
	v_fmac_f32_e32 v4, v5, v4
	v_div_scale_f32 v5, vcc, 1.0, v2, 1.0
	v_mul_f32_e32 v6, v5, v4
	v_fma_f32 v7, -v3, v6, v5
	v_fmac_f32_e32 v6, v7, v4
	v_fma_f32 v5, -v3, v6, v5
	s_nop 1
	v_div_fmas_f32 v3, v5, v4, v6
	v_div_fixup_f32 v9, v3, v2, 1.0
	s_cmp_lg_u32 s23, 0
	s_cbranch_scc1 .Lln1_nopub4
	s_mov_b64 s[26:27], exec
	s_mov_b64 exec, 0xffff
	v_add_u32_e32 v253, 0x400, v249
	global_store_dwordx2 v253, v[8:9], s[10:11]
	s_mov_b64 exec, s[26:27]
; __device__ __forceinline__ unsigned cvt_pk_bf16(float lo, float hi) { unsigned r; asm volatile("v_cvt_pk_bf16_f32 %0, %1, %2" : "=v"(r) : "v"(lo), "v"(hi)); return r; }
; __global__ void __launch_bounds__(512, 2) fwd_kernel(Args a) {
;     ...
;             const float rstd_a = 1.0f / sqrtf(wave_sum(qa) * (1.0f / DMODEL) + LN_EPS), rstd_b = 1.0f / sqrtf(wave_sum(qb_) * (1.0f / DMODEL) + LN_EPS);
;             u32x2* o8 = (u32x2*)(ubuf + (size_t)m * DMODEL) + lane;
;             f32x4 ggv[8], bbv[8], shv[8], scv[8];
; #pragma unroll
;             for (int j = 0; j < 8; ++j) { const int col = 4 * lane + 256 * j; ggv[j] = *(const f32x4*)(lng_p + col); bbv[j] = *(const f32x4*)(lnb_p + col);
;                 shv[j] = *(const f32x4*)(md + 3 * DMODEL + col); scv[j] = *(const f32x4*)(md + 4 * DMODEL + col); }
; #pragma unroll
;             for (int j = 0; j < 8; ++j) { const f32x4 gg = ggv[j], bb = bbv[j];
;                 const f32x4 ya = va[j] * rstd_a * gg + bb, yb = vb[j] * rstd_b * gg + bb; __builtin_nontemporal_store(ya, xr + 64 * j); __builtin_nontemporal_store(yb, xr + 512 + 64 * j);
;                 const f32x4 sh = shv[j], sc = scv[j] + 1.0f;
;                 const f32x4 ua = ya * sc + sh, ub = yb * sc + sh; u32x2 wa, wb;
;                 wa.x = pg8::cvt_pk_bf16(ua[0], ua[1]); wa.y = pg8::cvt_pk_bf16(ua[2], ua[3]); wb.x = pg8::cvt_pk_bf16(ub[0], ub[1]); wb.y = pg8::cvt_pk_bf16(ub[2], ub[3]);
;                 o8[64 * j] = wa; o8[512 + 64 * j] = wb; } }
.Lln1_nopub4:
	s_mov_b64 s[28:29], 0x80000
	v_lshl_add_u64 v[12:13], v[246:247], 0, s[28:29]
	v_pk_fma_f32 v[94:95], v[8:9], v[10:11], v[94:95] op_sel:[0,1,0] op_sel_hi:[0,1,1]
	v_pk_mul_f32 v[94:95], v[94:95], v[8:9] op_sel:[0,1] op_sel_hi:[1,1]
	v_pk_fma_f32 v[94:95], v[130:131], v[94:95], v[146:147]
	v_pk_fma_f32 v[94:95], v[94:95], v[178:179], v[162:163]
	v_pk_fma_f32 v[96:97], v[8:9], v[10:11], v[96:97] op_sel:[0,1,0] op_sel_hi:[0,1,1]
	v_pk_mul_f32 v[96:97], v[96:97], v[8:9] op_sel:[0,1] op_sel_hi:[1,1]
	v_pk_fma_f32 v[96:97], v[132:133], v[96:97], v[148:149]
	v_pk_fma_f32 v[96:97], v[96:97], v[180:181], v[164:165]
	v_cvt_pk_bf16_f32 v94, v94, v95
	v_cvt_pk_bf16_f32 v95, v96, v97
	global_store_dwordx2 v[12:13], v[94:95], off
	v_pk_fma_f32 v[90:91], v[8:9], v[10:11], v[90:91] op_sel:[0,1,0] op_sel_hi:[0,1,1]
	v_pk_mul_f32 v[90:91], v[90:91], v[8:9] op_sel:[0,1] op_sel_hi:[1,1]
	v_pk_fma_f32 v[90:91], v[134:135], v[90:91], v[150:151]
	v_pk_fma_f32 v[90:91], v[90:91], v[182:183], v[166:167]
	v_pk_fma_f32 v[92:93], v[8:9], v[10:11], v[92:93] op_sel:[0,1,0] op_sel_hi:[0,1,1]
	v_pk_mul_f32 v[92:93], v[92:93], v[8:9] op_sel:[0,1] op_sel_hi:[1,1]
	v_pk_fma_f32 v[92:93], v[136:137], v[92:93], v[152:153]
	v_pk_fma_f32 v[92:93], v[92:93], v[184:185], v[168:169]
	v_cvt_pk_bf16_f32 v90, v90, v91
	v_cvt_pk_bf16_f32 v91, v92, v93
	global_store_dwordx2 v[12:13], v[90:91], off offset:32
	v_pk_fma_f32 v[30:31], v[8:9], v[10:11], v[30:31] op_sel:[0,1,0] op_sel_hi:[0,1,1]
	v_pk_mul_f32 v[30:31], v[30:31], v[8:9] op_sel:[0,1] op_sel_hi:[1,1]
	v_pk_fma_f32 v[30:31], v[138:139], v[30:31], v[154:155]
	v_pk_fma_f32 v[30:31], v[30:31], v[186:187], v[170:171]
	v_pk_fma_f32 v[32:33], v[8:9], v[10:11], v[32:33] op_sel:[0,1,0] op_sel_hi:[0,1,1]
	v_pk_mul_f32 v[32:33], v[32:33], v[8:9] op_sel:[0,1] op_sel_hi:[1,1]
	v_pk_fma_f32 v[32:33], v[140:141], v[32:33], v[156:157]
	v_pk_fma_f32 v[32:33], v[32:33], v[188:189], v[172:173]
	v_cvt_pk_bf16_f32 v30, v30, v31
	v_cvt_pk_bf16_f32 v31, v32, v33
	global_store_dwordx2 v[12:13], v[30:31], off offset:256
	v_pk_fma_f32 v[26:27], v[8:9], v[10:11], v[26:27] op_sel:[0,1,0] op_sel_hi:[0,1,1]
	v_pk_mul_f32 v[26:27], v[26:27], v[8:9] op_sel:[0,1] op_sel_hi:[1,1]
	v_pk_fma_f32 v[26:27], v[142:143], v[26:27], v[158:159]
	v_pk_fma_f32 v[26:27], v[26:27], v[190:191], v[174:175]
	v_pk_fma_f32 v[28:29], v[8:9], v[10:11], v[28:29] op_sel:[0,1,0] op_sel_hi:[0,1,1]
	v_pk_mul_f32 v[28:29], v[28:29], v[8:9] op_sel:[0,1] op_sel_hi:[1,1]
	v_pk_fma_f32 v[28:29], v[144:145], v[28:29], v[160:161]
	v_pk_fma_f32 v[28:29], v[28:29], v[192:193], v[176:177]
	v_cvt_pk_bf16_f32 v26, v26, v27
	v_cvt_pk_bf16_f32 v27, v28, v29
	global_store_dwordx2 v[12:13], v[26:27], off offset:288
	v_add_u32_e32 v252, 0x2800, v248
	global_load_dwordx4 v[214:217], v252, s[8:9]
	global_load_dwordx4 v[218:221], v252, s[8:9] offset:16
	global_load_dwordx4 v[222:225], v252, s[8:9] offset:32
	global_load_dwordx4 v[226:229], v252, s[8:9] offset:48
	s_waitcnt vmcnt(8)
	v_add_f32_e32 v8, v230, v232
	v_add_f32_e32 v8, v8, v234
	v_add_f32_e32 v8, v8, v236
	v_add_f32_e32 v8, v8, v238
	v_add_f32_e32 v8, v8, v240
	v_add_f32_e32 v8, v8, v242
	v_add_f32_e32 v8, v8, v244
	v_mul_f32_e32 v14, 0x3a000000, v8
	v_add_f32_e32 v9, v231, v233
	v_add_f32_e32 v9, v9, v235
	v_add_f32_e32 v9, v9, v237
	v_add_f32_e32 v9, v9, v239
	v_add_f32_e32 v9, v9, v241
	v_add_f32_e32 v9, v9, v243
	v_add_f32_e32 v9, v9, v245
	v_fma_f32 v15, v230, s22, -v14
	v_mul_f32_e32 v15, v15, v15
	v_fmac_f32_e32 v9, 0x43800000, v15
	v_fma_f32 v15, v232, s22, -v14
	v_mul_f32_e32 v15, v15, v15
	v_fmac_f32_e32 v9, 0x43800000, v15
	v_fma_f32 v15, v234, s22, -v14
	v_mul_f32_e32 v15, v15, v15
	v_fmac_f32_e32 v9, 0x43800000, v15
	v_fma_f32 v15, v236, s22, -v14
	v_mul_f32_e32 v15, v15, v15
	v_fmac_f32_e32 v9, 0x43800000, v15
	v_fma_f32 v15, v238, s22, -v14
	v_mul_f32_e32 v15, v15, v15
	v_fmac_f32_e32 v9, 0x43800000, v15
	v_fma_f32 v15, v240, s22, -v14
	v_mul_f32_e32 v15, v15, v15
	v_fmac_f32_e32 v9, 0x43800000, v15
	v_fma_f32 v15, v242, s22, -v14
	v_mul_f32_e32 v15, v15, v15
	v_fmac_f32_e32 v9, 0x43800000, v15
	v_fma_f32 v15, v244, s22, -v14
	v_mul_f32_e32 v15, v15, v15
	v_fmac_f32_e32 v9, 0x43800000, v15
	v_fmamk_f32 v9, v9, 0x3a000000, v250
	v_mul_f32_e32 v15, 0x4f800000, v9
	v_cmp_gt_f32_e32 vcc, s15, v9
	s_nop 1
	v_cndmask_b32_e32 v2, v9, v15, vcc
	v_sqrt_f32_e32 v3, v2
	s_nop 1
	v_add_u32_e32 v4, -1, v3
	v_fma_f32 v5, -v4, v3, v2
	v_cmp_ge_f32_e64 s[24:25], 0, v5
	v_add_u32_e32 v5, 1, v3
	v_fma_f32 v6, -v5, v3, v2
	s_nop 0
	v_cndmask_b32_e64 v4, v3, v4, s[24:25]
	v_cmp_lt_f32_e64 s[24:25], 0, v6
	s_nop 1
	v_cndmask_b32_e64 v4, v4, v5, s[24:25]
	v_mul_f32_e32 v5, 0x37800000, v4
	v_cndmask_b32_e32 v4, v4, v5, vcc
	v_cmp_class_f32_e32 vcc, v2, v251
	s_nop 1
	v_cndmask_b32_e32 v2, v4, v2, vcc
	v_div_scale_f32 v3, s[24:25], v2, v2, 1.0
	v_rcp_f32_e32 v4, v3
	s_nop 1
	v_fma_f32 v5, -v3, v4, 1.0
	v_fmac_f32_e32 v4, v5, v4
	v_div_scale_f32 v5, vcc, 1.0, v2, 1.0
	v_mul_f32_e32 v6, v5, v4
	v_fma_f32 v7, -v3, v6, v5
	v_fmac_f32_e32 v6, v7, v4
	v_fma_f32 v5, -v3, v6, v5
	s_nop 1
	v_div_fmas_f32 v3, v5, v4, v6
	v_div_fixup_f32 v9, v3, v2, 1.0
	s_cmp_lg_u32 s23, 0
	s_cbranch_scc1 .Lln1_nopub5
	s_mov_b64 s[26:27], exec
	s_mov_b64 exec, 0xffff
	v_add_u32_e32 v253, 0x480, v249
	global_store_dwordx2 v253, v[8:9], s[10:11]
	s_mov_b64 exec, s[26:27]
; __device__ __forceinline__ unsigned cvt_pk_bf16(float lo, float hi) { unsigned r; asm volatile("v_cvt_pk_bf16_f32 %0, %1, %2" : "=v"(r) : "v"(lo), "v"(hi)); return r; }
; __global__ void __launch_bounds__(512, 2) fwd_kernel(Args a) {
;     ...
;             const float rstd_a = 1.0f / sqrtf(wave_sum(qa) * (1.0f / DMODEL) + LN_EPS), rstd_b = 1.0f / sqrtf(wave_sum(qb_) * (1.0f / DMODEL) + LN_EPS);
;             u32x2* o8 = (u32x2*)(ubuf + (size_t)m * DMODEL) + lane;
;             f32x4 ggv[8], bbv[8], shv[8], scv[8];
; #pragma unroll
;             for (int j = 0; j < 8; ++j) { const int col = 4 * lane + 256 * j; ggv[j] = *(const f32x4*)(lng_p + col); bbv[j] = *(const f32x4*)(lnb_p + col);
;                 shv[j] = *(const f32x4*)(md + 3 * DMODEL + col); scv[j] = *(const f32x4*)(md + 4 * DMODEL + col); }
; #pragma unroll
;             for (int j = 0; j < 8; ++j) { const f32x4 gg = ggv[j], bb = bbv[j];
;                 const f32x4 ya = va[j] * rstd_a * gg + bb, yb = vb[j] * rstd_b * gg + bb; __builtin_nontemporal_store(ya, xr + 64 * j); __builtin_nontemporal_store(yb, xr + 512 + 64 * j);
;                 const f32x4 sh = shv[j], sc = scv[j] + 1.0f;
;                 const f32x4 ua = ya * sc + sh, ub = yb * sc + sh; u32x2 wa, wb;
;                 wa.x = pg8::cvt_pk_bf16(ua[0], ua[1]); wa.y = pg8::cvt_pk_bf16(ua[2], ua[3]); wb.x = pg8::cvt_pk_bf16(ub[0], ub[1]); wb.y = pg8::cvt_pk_bf16(ub[2], ub[3]);
;                 o8[64 * j] = wa; o8[512 + 64 * j] = wb; } }
.Lln1_nopub5:
	s_mov_b64 s[28:29], 0x90000
	v_lshl_add_u64 v[12:13], v[246:247], 0, s[28:29]
	v_pk_fma_f32 v[86:87], v[8:9], v[10:11], v[86:87] op_sel:[0,1,0] op_sel_hi:[0,1,1]
	v_pk_mul_f32 v[86:87], v[86:87], v[8:9] op_sel:[0,1] op_sel_hi:[1,1]
	v_pk_fma_f32 v[86:87], v[130:131], v[86:87], v[146:147]
	v_pk_fma_f32 v[86:87], v[86:87], v[178:179], v[162:163]
	v_pk_fma_f32 v[88:89], v[8:9], v[10:11], v[88:89] op_sel:[0,1,0] op_sel_hi:[0,1,1]
	v_pk_mul_f32 v[88:89], v[88:89], v[8:9] op_sel:[0,1] op_sel_hi:[1,1]
	v_pk_fma_f32 v[88:89], v[132:133], v[88:89], v[148:149]
	v_pk_fma_f32 v[88:89], v[88:89], v[180:181], v[164:165]
	v_cvt_pk_bf16_f32 v86, v86, v87
	v_cvt_pk_bf16_f32 v87, v88, v89
	global_store_dwordx2 v[12:13], v[86:87], off
	v_pk_fma_f32 v[82:83], v[8:9], v[10:11], v[82:83] op_sel:[0,1,0] op_sel_hi:[0,1,1]
	v_pk_mul_f32 v[82:83], v[82:83], v[8:9] op_sel:[0,1] op_sel_hi:[1,1]
	v_pk_fma_f32 v[82:83], v[134:135], v[82:83], v[150:151]
	v_pk_fma_f32 v[82:83], v[82:83], v[182:183], v[166:167]
	v_pk_fma_f32 v[84:85], v[8:9], v[10:11], v[84:85] op_sel:[0,1,0] op_sel_hi:[0,1,1]
	v_pk_mul_f32 v[84:85], v[84:85], v[8:9] op_sel:[0,1] op_sel_hi:[1,1]
	v_pk_fma_f32 v[84:85], v[136:137], v[84:85], v[152:153]
	v_pk_fma_f32 v[84:85], v[84:85], v[184:185], v[168:169]
	v_cvt_pk_bf16_f32 v82, v82, v83
	v_cvt_pk_bf16_f32 v83, v84, v85
	global_store_dwordx2 v[12:13], v[82:83], off offset:32
	v_pk_fma_f32 v[22:23], v[8:9], v[10:11], v[22:23] op_sel:[0,1,0] op_sel_hi:[0,1,1]
	v_pk_mul_f32 v[22:23], v[22:23], v[8:9] op_sel:[0,1] op_sel_hi:[1,1]
	v_pk_fma_f32 v[22:23], v[138:139], v[22:23], v[154:155]
	v_pk_fma_f32 v[22:23], v[22:23], v[186:187], v[170:171]
	v_pk_fma_f32 v[24:25], v[8:9], v[10:11], v[24:25] op_sel:[0,1,0] op_sel_hi:[0,1,1]
	v_pk_mul_f32 v[24:25], v[24:25], v[8:9] op_sel:[0,1] op_sel_hi:[1,1]
	v_pk_fma_f32 v[24:25], v[140:141], v[24:25], v[156:157]
	v_pk_fma_f32 v[24:25], v[24:25], v[188:189], v[172:173]
	v_cvt_pk_bf16_f32 v22, v22, v23
	v_cvt_pk_bf16_f32 v23, v24, v25
	global_store_dwordx2 v[12:13], v[22:23], off offset:256
	v_pk_fma_f32 v[18:19], v[8:9], v[10:11], v[18:19] op_sel:[0,1,0] op_sel_hi:[0,1,1]
	v_pk_mul_f32 v[18:19], v[18:19], v[8:9] op_sel:[0,1] op_sel_hi:[1,1]
	v_pk_fma_f32 v[18:19], v[142:143], v[18:19], v[158:159]
	v_pk_fma_f32 v[18:19], v[18:19], v[190:191], v[174:175]
	v_pk_fma_f32 v[20:21], v[8:9], v[10:11], v[20:21] op_sel:[0,1,0] op_sel_hi:[0,1,1]
	v_pk_mul_f32 v[20:21], v[20:21], v[8:9] op_sel:[0,1] op_sel_hi:[1,1]
	v_pk_fma_f32 v[20:21], v[144:145], v[20:21], v[160:161]
	v_pk_fma_f32 v[20:21], v[20:21], v[192:193], v[176:177]
	v_cvt_pk_bf16_f32 v18, v18, v19
	v_cvt_pk_bf16_f32 v19, v20, v21
	global_store_dwordx2 v[12:13], v[18:19], off offset:288
	v_add_u32_e32 v252, 0x2c00, v248
	global_load_dwordx4 v[230:233], v252, s[8:9]
	global_load_dwordx4 v[234:237], v252, s[8:9] offset:16
	global_load_dwordx4 v[238:241], v252, s[8:9] offset:32
	global_load_dwordx4 v[242:245], v252, s[8:9] offset:48
	s_waitcnt vmcnt(8)
	v_add_f32_e32 v8, v214, v216
	v_add_f32_e32 v8, v8, v218
	v_add_f32_e32 v8, v8, v220
	v_add_f32_e32 v8, v8, v222
	v_add_f32_e32 v8, v8, v224
	v_add_f32_e32 v8, v8, v226
	v_add_f32_e32 v8, v8, v228
	v_mul_f32_e32 v14, 0x3a000000, v8
	v_add_f32_e32 v9, v215, v217
	v_add_f32_e32 v9, v9, v219
	v_add_f32_e32 v9, v9, v221
	v_add_f32_e32 v9, v9, v223
	v_add_f32_e32 v9, v9, v225
	v_add_f32_e32 v9, v9, v227
	v_add_f32_e32 v9, v9, v229
	v_fma_f32 v15, v214, s22, -v14
	v_mul_f32_e32 v15, v15, v15
	v_fmac_f32_e32 v9, 0x43800000, v15
	v_fma_f32 v15, v216, s22, -v14
	v_mul_f32_e32 v15, v15, v15
	v_fmac_f32_e32 v9, 0x43800000, v15
	v_fma_f32 v15, v218, s22, -v14
	v_mul_f32_e32 v15, v15, v15
	v_fmac_f32_e32 v9, 0x43800000, v15
	v_fma_f32 v15, v220, s22, -v14
	v_mul_f32_e32 v15, v15, v15
	v_fmac_f32_e32 v9, 0x43800000, v15
	v_fma_f32 v15, v222, s22, -v14
	v_mul_f32_e32 v15, v15, v15
	v_fmac_f32_e32 v9, 0x43800000, v15
	v_fma_f32 v15, v224, s22, -v14
	v_mul_f32_e32 v15, v15, v15
	v_fmac_f32_e32 v9, 0x43800000, v15
	v_fma_f32 v15, v226, s22, -v14
	v_mul_f32_e32 v15, v15, v15
	v_fmac_f32_e32 v9, 0x43800000, v15
	v_fma_f32 v15, v228, s22, -v14
	v_mul_f32_e32 v15, v15, v15
	v_fmac_f32_e32 v9, 0x43800000, v15
	v_fmamk_f32 v9, v9, 0x3a000000, v250
	v_mul_f32_e32 v15, 0x4f800000, v9
	v_cmp_gt_f32_e32 vcc, s15, v9
	s_nop 1
	v_cndmask_b32_e32 v2, v9, v15, vcc
	v_sqrt_f32_e32 v3, v2
	s_nop 1
	v_add_u32_e32 v4, -1, v3
	v_fma_f32 v5, -v4, v3, v2
	v_cmp_ge_f32_e64 s[24:25], 0, v5
	v_add_u32_e32 v5, 1, v3
	v_fma_f32 v6, -v5, v3, v2
	s_nop 0
	v_cndmask_b32_e64 v4, v3, v4, s[24:25]
	v_cmp_lt_f32_e64 s[24:25], 0, v6
	s_nop 1
	v_cndmask_b32_e64 v4, v4, v5, s[24:25]
	v_mul_f32_e32 v5, 0x37800000, v4
	v_cndmask_b32_e32 v4, v4, v5, vcc
	v_cmp_class_f32_e32 vcc, v2, v251
	s_nop 1
	v_cndmask_b32_e32 v2, v4, v2, vcc
	v_div_scale_f32 v3, s[24:25], v2, v2, 1.0
	v_rcp_f32_e32 v4, v3
	s_nop 1
	v_fma_f32 v5, -v3, v4, 1.0
	v_fmac_f32_e32 v4, v5, v4
	v_div_scale_f32 v5, vcc, 1.0, v2, 1.0
	v_mul_f32_e32 v6, v5, v4
	v_fma_f32 v7, -v3, v6, v5
	v_fmac_f32_e32 v6, v7, v4
	v_fma_f32 v5, -v3, v6, v5
	s_nop 1
	v_div_fmas_f32 v3, v5, v4, v6
	v_div_fixup_f32 v9, v3, v2, 1.0
	s_cmp_lg_u32 s23, 0
	s_cbranch_scc1 .Lln1_nopub6
	s_mov_b64 s[26:27], exec
	s_mov_b64 exec, 0xffff
	v_add_u32_e32 v253, 0x500, v249
	global_store_dwordx2 v253, v[8:9], s[10:11]
	s_mov_b64 exec, s[26:27]
; __device__ __forceinline__ unsigned cvt_pk_bf16(float lo, float hi) { unsigned r; asm volatile("v_cvt_pk_bf16_f32 %0, %1, %2" : "=v"(r) : "v"(lo), "v"(hi)); return r; }
; __global__ void __launch_bounds__(512, 2) fwd_kernel(Args a) {
;     ...
;             const float rstd_a = 1.0f / sqrtf(wave_sum(qa) * (1.0f / DMODEL) + LN_EPS), rstd_b = 1.0f / sqrtf(wave_sum(qb_) * (1.0f / DMODEL) + LN_EPS);
;             u32x2* o8 = (u32x2*)(ubuf + (size_t)m * DMODEL) + lane;
;             f32x4 ggv[8], bbv[8], shv[8], scv[8];
; #pragma unroll
;             for (int j = 0; j < 8; ++j) { const int col = 4 * lane + 256 * j; ggv[j] = *(const f32x4*)(lng_p + col); bbv[j] = *(const f32x4*)(lnb_p + col);
;                 shv[j] = *(const f32x4*)(md + 3 * DMODEL + col); scv[j] = *(const f32x4*)(md + 4 * DMODEL + col); }
; #pragma unroll
;             for (int j = 0; j < 8; ++j) { const f32x4 gg = ggv[j], bb = bbv[j];
;                 const f32x4 ya = va[j] * rstd_a * gg + bb, yb = vb[j] * rstd_b * gg + bb; __builtin_nontemporal_store(ya, xr + 64 * j); __builtin_nontemporal_store(yb, xr + 512 + 64 * j);
;                 const f32x4 sh = shv[j], sc = scv[j] + 1.0f;
;                 const f32x4 ua = ya * sc + sh, ub = yb * sc + sh; u32x2 wa, wb;
;                 wa.x = pg8::cvt_pk_bf16(ua[0], ua[1]); wa.y = pg8::cvt_pk_bf16(ua[2], ua[3]); wb.x = pg8::cvt_pk_bf16(ub[0], ub[1]); wb.y = pg8::cvt_pk_bf16(ub[2], ub[3]);
;                 o8[64 * j] = wa; o8[512 + 64 * j] = wb; } }
.Lln1_nopub6:
	s_mov_b64 s[28:29], 0xa0000
	v_lshl_add_u64 v[12:13], v[246:247], 0, s[28:29]
	v_pk_fma_f32 v[78:79], v[8:9], v[10:11], v[78:79] op_sel:[0,1,0] op_sel_hi:[0,1,1]
	v_pk_mul_f32 v[78:79], v[78:79], v[8:9] op_sel:[0,1] op_sel_hi:[1,1]
	v_pk_fma_f32 v[78:79], v[130:131], v[78:79], v[146:147]
	v_pk_fma_f32 v[78:79], v[78:79], v[178:179], v[162:163]
	v_pk_fma_f32 v[80:81], v[8:9], v[10:11], v[80:81] op_sel:[0,1,0] op_sel_hi:[0,1,1]
	v_pk_mul_f32 v[80:81], v[80:81], v[8:9] op_sel:[0,1] op_sel_hi:[1,1]
	v_pk_fma_f32 v[80:81], v[132:133], v[80:81], v[148:149]
	v_pk_fma_f32 v[80:81], v[80:81], v[180:181], v[164:165]
	v_cvt_pk_bf16_f32 v78, v78, v79
	v_cvt_pk_bf16_f32 v79, v80, v81
	global_store_dwordx2 v[12:13], v[78:79], off
	v_pk_fma_f32 v[74:75], v[8:9], v[10:11], v[74:75] op_sel:[0,1,0] op_sel_hi:[0,1,1]
	v_pk_mul_f32 v[74:75], v[74:75], v[8:9] op_sel:[0,1] op_sel_hi:[1,1]
	v_pk_fma_f32 v[74:75], v[134:135], v[74:75], v[150:151]
	v_pk_fma_f32 v[74:75], v[74:75], v[182:183], v[166:167]
	v_pk_fma_f32 v[76:77], v[8:9], v[10:11], v[76:77] op_sel:[0,1,0] op_sel_hi:[0,1,1]
	v_pk_mul_f32 v[76:77], v[76:77], v[8:9] op_sel:[0,1] op_sel_hi:[1,1]
	v_pk_fma_f32 v[76:77], v[136:137], v[76:77], v[152:153]
	v_pk_fma_f32 v[76:77], v[76:77], v[184:185], v[168:169]
	v_cvt_pk_bf16_f32 v74, v74, v75
	v_cvt_pk_bf16_f32 v75, v76, v77
	global_store_dwordx2 v[12:13], v[74:75], off offset:32
	v_pk_fma_f32 v[210:211], v[8:9], v[10:11], v[210:211] op_sel:[0,1,0] op_sel_hi:[0,1,1]
	v_pk_mul_f32 v[210:211], v[210:211], v[8:9] op_sel:[0,1] op_sel_hi:[1,1]
	v_pk_fma_f32 v[210:211], v[138:139], v[210:211], v[154:155]
	v_pk_fma_f32 v[210:211], v[210:211], v[186:187], v[170:171]
	v_pk_fma_f32 v[212:213], v[8:9], v[10:11], v[212:213] op_sel:[0,1,0] op_sel_hi:[0,1,1]
	v_pk_mul_f32 v[212:213], v[212:213], v[8:9] op_sel:[0,1] op_sel_hi:[1,1]
	v_pk_fma_f32 v[212:213], v[140:141], v[212:213], v[156:157]
	v_pk_fma_f32 v[212:213], v[212:213], v[188:189], v[172:173]
	v_cvt_pk_bf16_f32 v210, v210, v211
	v_cvt_pk_bf16_f32 v211, v212, v213
	global_store_dwordx2 v[12:13], v[210:211], off offset:256
	v_pk_fma_f32 v[206:207], v[8:9], v[10:11], v[206:207] op_sel:[0,1,0] op_sel_hi:[0,1,1]
	v_pk_mul_f32 v[206:207], v[206:207], v[8:9] op_sel:[0,1] op_sel_hi:[1,1]
	v_pk_fma_f32 v[206:207], v[142:143], v[206:207], v[158:159]
	v_pk_fma_f32 v[206:207], v[206:207], v[190:191], v[174:175]
	v_pk_fma_f32 v[208:209], v[8:9], v[10:11], v[208:209] op_sel:[0,1,0] op_sel_hi:[0,1,1]
	v_pk_mul_f32 v[208:209], v[208:209], v[8:9] op_sel:[0,1] op_sel_hi:[1,1]
	v_pk_fma_f32 v[208:209], v[144:145], v[208:209], v[160:161]
	v_pk_fma_f32 v[208:209], v[208:209], v[192:193], v[176:177]
	v_cvt_pk_bf16_f32 v206, v206, v207
	v_cvt_pk_bf16_f32 v207, v208, v209
	global_store_dwordx2 v[12:13], v[206:207], off offset:288
	s_waitcnt vmcnt(4)
	v_add_f32_e32 v8, v230, v232
	v_add_f32_e32 v8, v8, v234
	v_add_f32_e32 v8, v8, v236
	v_add_f32_e32 v8, v8, v238
	v_add_f32_e32 v8, v8, v240
	v_add_f32_e32 v8, v8, v242
	v_add_f32_e32 v8, v8, v244
	v_mul_f32_e32 v14, 0x3a000000, v8
	v_add_f32_e32 v9, v231, v233
	v_add_f32_e32 v9, v9, v235
	v_add_f32_e32 v9, v9, v237
	v_add_f32_e32 v9, v9, v239
	v_add_f32_e32 v9, v9, v241
	v_add_f32_e32 v9, v9, v243
	v_add_f32_e32 v9, v9, v245
	v_fma_f32 v15, v230, s22, -v14
	v_mul_f32_e32 v15, v15, v15
	v_fmac_f32_e32 v9, 0x43800000, v15
	v_fma_f32 v15, v232, s22, -v14
	v_mul_f32_e32 v15, v15, v15
	v_fmac_f32_e32 v9, 0x43800000, v15
	v_fma_f32 v15, v234, s22, -v14
	v_mul_f32_e32 v15, v15, v15
	v_fmac_f32_e32 v9, 0x43800000, v15
	v_fma_f32 v15, v236, s22, -v14
	v_mul_f32_e32 v15, v15, v15
	v_fmac_f32_e32 v9, 0x43800000, v15
	v_fma_f32 v15, v238, s22, -v14
	v_mul_f32_e32 v15, v15, v15
	v_fmac_f32_e32 v9, 0x43800000, v15
	v_fma_f32 v15, v240, s22, -v14
	v_mul_f32_e32 v15, v15, v15
	v_fmac_f32_e32 v9, 0x43800000, v15
	v_fma_f32 v15, v242, s22, -v14
	v_mul_f32_e32 v15, v15, v15
	v_fmac_f32_e32 v9, 0x43800000, v15
	v_fma_f32 v15, v244, s22, -v14
	v_mul_f32_e32 v15, v15, v15
	v_fmac_f32_e32 v9, 0x43800000, v15
	v_fmamk_f32 v9, v9, 0x3a000000, v250
	v_mul_f32_e32 v15, 0x4f800000, v9
	v_cmp_gt_f32_e32 vcc, s15, v9
	s_nop 1
	v_cndmask_b32_e32 v2, v9, v15, vcc
	v_sqrt_f32_e32 v3, v2
	s_nop 1
	v_add_u32_e32 v4, -1, v3
	v_fma_f32 v5, -v4, v3, v2
	v_cmp_ge_f32_e64 s[24:25], 0, v5
	v_add_u32_e32 v5, 1, v3
	v_fma_f32 v6, -v5, v3, v2
	s_nop 0
	v_cndmask_b32_e64 v4, v3, v4, s[24:25]
	v_cmp_lt_f32_e64 s[24:25], 0, v6
	s_nop 1
	v_cndmask_b32_e64 v4, v4, v5, s[24:25]
	v_mul_f32_e32 v5, 0x37800000, v4
	v_cndmask_b32_e32 v4, v4, v5, vcc
	v_cmp_class_f32_e32 vcc, v2, v251
	s_nop 1
	v_cndmask_b32_e32 v2, v4, v2, vcc
	v_div_scale_f32 v3, s[24:25], v2, v2, 1.0
	v_rcp_f32_e32 v4, v3
	s_nop 1
	v_fma_f32 v5, -v3, v4, 1.0
	v_fmac_f32_e32 v4, v5, v4
	v_div_scale_f32 v5, vcc, 1.0, v2, 1.0
	v_mul_f32_e32 v6, v5, v4
	v_fma_f32 v7, -v3, v6, v5
	v_fmac_f32_e32 v6, v7, v4
	v_fma_f32 v5, -v3, v6, v5
	s_nop 1
	v_div_fmas_f32 v3, v5, v4, v6
	v_div_fixup_f32 v9, v3, v2, 1.0
	s_cmp_lg_u32 s23, 0
	s_cbranch_scc1 .Lln1_nopub7
	s_mov_b64 s[26:27], exec
	s_mov_b64 exec, 0xffff
	v_add_u32_e32 v253, 0x580, v249
	global_store_dwordx2 v253, v[8:9], s[10:11]
	s_mov_b64 exec, s[26:27]
; __device__ __forceinline__ unsigned cvt_pk_bf16(float lo, float hi) { unsigned r; asm volatile("v_cvt_pk_bf16_f32 %0, %1, %2" : "=v"(r) : "v"(lo), "v"(hi)); return r; }
; __global__ void __launch_bounds__(512, 2) fwd_kernel(Args a) {
;     ...
;             for (int j = 0; j < 8; ++j) { const f32x4 gg = ggv[j], bb = bbv[j];
;                 const f32x4 ya = va[j] * rstd_a * gg + bb, yb = vb[j] * rstd_b * gg + bb; __builtin_nontemporal_store(ya, xr + 64 * j); __builtin_nontemporal_store(yb, xr + 512 + 64 * j);
;                 const f32x4 sh = shv[j], sc = scv[j] + 1.0f;
;                 const f32x4 ua = ya * sc + sh, ub = yb * sc + sh; u32x2 wa, wb;
;                 wa.x = pg8::cvt_pk_bf16(ua[0], ua[1]); wa.y = pg8::cvt_pk_bf16(ua[2], ua[3]); wb.x = pg8::cvt_pk_bf16(ub[0], ub[1]); wb.y = pg8::cvt_pk_bf16(ub[2], ub[3]);
;                 o8[64 * j] = wa; o8[512 + 64 * j] = wb; } }
.Lln1_nopub7:
	s_mov_b64 s[28:29], 0xb0000
	v_lshl_add_u64 v[12:13], v[246:247], 0, s[28:29]
	v_pk_fma_f32 v[70:71], v[8:9], v[10:11], v[70:71] op_sel:[0,1,0] op_sel_hi:[0,1,1]
	v_pk_mul_f32 v[70:71], v[70:71], v[8:9] op_sel:[0,1] op_sel_hi:[1,1]
	v_pk_fma_f32 v[70:71], v[130:131], v[70:71], v[146:147]
	v_pk_fma_f32 v[70:71], v[70:71], v[178:179], v[162:163]
	v_pk_fma_f32 v[72:73], v[8:9], v[10:11], v[72:73] op_sel:[0,1,0] op_sel_hi:[0,1,1]
	v_pk_mul_f32 v[72:73], v[72:73], v[8:9] op_sel:[0,1] op_sel_hi:[1,1]
	v_pk_fma_f32 v[72:73], v[132:133], v[72:73], v[148:149]
	v_pk_fma_f32 v[72:73], v[72:73], v[180:181], v[164:165]
	v_cvt_pk_bf16_f32 v70, v70, v71
	v_cvt_pk_bf16_f32 v71, v72, v73
	global_store_dwordx2 v[12:13], v[70:71], off
	v_pk_fma_f32 v[66:67], v[8:9], v[10:11], v[66:67] op_sel:[0,1,0] op_sel_hi:[0,1,1]
	v_pk_mul_f32 v[66:67], v[66:67], v[8:9] op_sel:[0,1] op_sel_hi:[1,1]
	v_pk_fma_f32 v[66:67], v[134:135], v[66:67], v[150:151]
	v_pk_fma_f32 v[66:67], v[66:67], v[182:183], v[166:167]
	v_pk_fma_f32 v[68:69], v[8:9], v[10:11], v[68:69] op_sel:[0,1,0] op_sel_hi:[0,1,1]
	v_pk_mul_f32 v[68:69], v[68:69], v[8:9] op_sel:[0,1] op_sel_hi:[1,1]
	v_pk_fma_f32 v[68:69], v[136:137], v[68:69], v[152:153]
	v_pk_fma_f32 v[68:69], v[68:69], v[184:185], v[168:169]
	v_cvt_pk_bf16_f32 v66, v66, v67
	v_cvt_pk_bf16_f32 v67, v68, v69
	global_store_dwordx2 v[12:13], v[66:67], off offset:32
	v_pk_fma_f32 v[202:203], v[8:9], v[10:11], v[202:203] op_sel:[0,1,0] op_sel_hi:[0,1,1]
	v_pk_mul_f32 v[202:203], v[202:203], v[8:9] op_sel:[0,1] op_sel_hi:[1,1]
	v_pk_fma_f32 v[202:203], v[138:139], v[202:203], v[154:155]
	v_pk_fma_f32 v[202:203], v[202:203], v[186:187], v[170:171]
	v_pk_fma_f32 v[204:205], v[8:9], v[10:11], v[204:205] op_sel:[0,1,0] op_sel_hi:[0,1,1]
	v_pk_mul_f32 v[204:205], v[204:205], v[8:9] op_sel:[0,1] op_sel_hi:[1,1]
	v_pk_fma_f32 v[204:205], v[140:141], v[204:205], v[156:157]
	v_pk_fma_f32 v[204:205], v[204:205], v[188:189], v[172:173]
	v_cvt_pk_bf16_f32 v202, v202, v203
	v_cvt_pk_bf16_f32 v203, v204, v205
	global_store_dwordx2 v[12:13], v[202:203], off offset:256
	v_pk_fma_f32 v[198:199], v[8:9], v[10:11], v[198:199] op_sel:[0,1,0] op_sel_hi:[0,1,1]
	v_pk_mul_f32 v[198:199], v[198:199], v[8:9] op_sel:[0,1] op_sel_hi:[1,1]
	v_pk_fma_f32 v[198:199], v[142:143], v[198:199], v[158:159]
	v_pk_fma_f32 v[198:199], v[198:199], v[190:191], v[174:175]
	v_pk_fma_f32 v[200:201], v[8:9], v[10:11], v[200:201] op_sel:[0,1,0] op_sel_hi:[0,1,1]
	v_pk_mul_f32 v[200:201], v[200:201], v[8:9] op_sel:[0,1] op_sel_hi:[1,1]
	v_pk_fma_f32 v[200:201], v[144:145], v[200:201], v[160:161]
	v_pk_fma_f32 v[200:201], v[200:201], v[192:193], v[176:177]
	v_cvt_pk_bf16_f32 v198, v198, v199
	v_cvt_pk_bf16_f32 v199, v200, v201
	global_store_dwordx2 v[12:13], v[198:199], off offset:288
